# closing K-loop barrier issued directly after the last MFMA (s_setprio 0 moved behind it), on top of the loop-edge and tight opening transition
# speedup vs baseline: 1.0081x; 1.0012x over previous
.Lt13b_0:
	s_barrier
	s_setprio 0
	s_mov_b32 m0, s13
	v_lshl_add_u64 v[208:209], s[8:9], 0, v[2:3]
	s_add_u32 s46, s8, 0x80000
	ds_read_b128 v[176:179], v143 offset:16384
	ds_read_b128 v[180:183], v143 offset:17408
	ds_read_b128 v[184:187], v143 offset:18432
	ds_read_b128 v[188:191], v143 offset:19456
	ds_read_b128 v[192:195], v143 offset:20480
	ds_read_b128 v[196:199], v143 offset:21504
	ds_read_b128 v[200:203], v143 offset:22528
	ds_read_b128 v[204:207], v143 offset:23552
	global_load_lds_dwordx4 v[208:209], off
	v_lshl_add_u64 v[210:211], s[8:9], 0, v[136:137]
	s_mov_b32 m0, s14
	s_addc_u32 s47, s9, 0
	global_load_lds_dwordx4 v[210:211], off
	v_lshl_add_u64 v[216:217], s[46:47], 0, v[2:3]
	s_mov_b32 m0, s15
	v_lshl_add_u64 v[218:219], s[10:11], 0, v[134:135]
	global_load_lds_dwordx4 v[216:217], off
	v_lshl_add_u64 v[216:217], s[46:47], 0, v[136:137]
	s_mov_b32 m0, s19
	s_nop 0
	global_load_lds_dwordx4 v[216:217], off
	v_lshl_add_u64 v[216:217], s[10:11], 0, v[132:133]
	s_mov_b32 m0, s16
	s_nop 0
	global_load_lds_dwordx4 v[216:217], off
	s_mov_b32 m0, s20
	s_nop 0
	global_load_lds_dwordx4 v[218:219], off
	s_waitcnt vmcnt(8)
	s_waitcnt lgkmcnt(0)
	s_setprio 1
	s_barrier
	s_cmp_lg_u32 s101, 0
	s_cbranch_scc1 .Lt13a_1
	v_mfma_f32_16x16x32_bf16 v[64:67], v[144:147], v[176:179], v[64:67]
	v_mfma_f32_16x16x32_bf16 v[64:67], v[148:151], v[180:183], v[64:67]
	v_mfma_f32_16x16x32_bf16 v[48:51], v[144:147], v[184:187], v[48:51]
	v_mfma_f32_16x16x32_bf16 v[48:51], v[148:151], v[188:191], v[48:51]
	v_mfma_f32_16x16x32_bf16 v[32:35], v[144:147], v[192:195], v[32:35]
	v_mfma_f32_16x16x32_bf16 v[32:35], v[148:151], v[196:199], v[32:35]
	v_mfma_f32_16x16x32_bf16 v[16:19], v[144:147], v[200:203], v[16:19]
	v_mfma_f32_16x16x32_bf16 v[16:19], v[148:151], v[204:207], v[16:19]
	v_mfma_f32_16x16x32_bf16 v[12:15], v[152:155], v[200:203], v[12:15]
	v_mfma_f32_16x16x32_bf16 v[12:15], v[156:159], v[204:207], v[12:15]
	v_mfma_f32_16x16x32_bf16 v[28:31], v[152:155], v[192:195], v[28:31]
	v_mfma_f32_16x16x32_bf16 v[28:31], v[156:159], v[196:199], v[28:31]
	v_mfma_f32_16x16x32_bf16 v[44:47], v[152:155], v[184:187], v[44:47]
	v_mfma_f32_16x16x32_bf16 v[44:47], v[156:159], v[188:191], v[44:47]
	v_mfma_f32_16x16x32_bf16 v[60:63], v[152:155], v[176:179], v[60:63]
	v_mfma_f32_16x16x32_bf16 v[60:63], v[156:159], v[180:183], v[60:63]

.Lt13b_1:
	s_barrier
	s_setprio 0
	v_add_u32_e32 v156, s45, v142
	v_add_u32_e32 v172, s74, v142
	ds_read_b128 v[144:147], v156
	ds_read_b128 v[148:151], v156 offset:1024
	ds_read_b128 v[152:155], v156 offset:2048
	ds_read_b128 v[156:159], v156 offset:3072
	ds_read_b128 v[160:163], v172
	ds_read_b128 v[164:167], v172 offset:1024
	ds_read_b128 v[168:171], v172 offset:2048
	ds_read_b128 v[172:175], v172 offset:3072
	s_add_u32 s10, s10, 0x80000
	s_addc_u32 s11, s11, 0
	s_mov_b32 m0, s22
	v_lshl_add_u64 v[220:221], s[10:11], 0, v[132:133]
	ds_read_b128 v[176:179], v143 offset:32768
	ds_read_b128 v[180:183], v143 offset:33792
	ds_read_b128 v[184:187], v143 offset:34816
	ds_read_b128 v[188:191], v143 offset:35840
	ds_read_b128 v[192:195], v143 offset:36864
	ds_read_b128 v[196:199], v143 offset:37888
	ds_read_b128 v[200:203], v143 offset:38912
	ds_read_b128 v[204:207], v143 offset:39936
	global_load_lds_dwordx4 v[220:221], off
	v_lshl_add_u64 v[220:221], s[10:11], 0, v[134:135]
	s_mov_b32 m0, s23
	s_nop 0
	global_load_lds_dwordx4 v[220:221], off
	s_waitcnt vmcnt(8)
	s_waitcnt lgkmcnt(0)
	s_setprio 1
	s_barrier
	s_cmp_lg_u32 s101, 0
	s_cbranch_scc1 .Lt13a_2
	v_mfma_f32_16x16x32_bf16 v[128:131], v[144:147], v[176:179], v[128:131]
	v_mfma_f32_16x16x32_bf16 v[128:131], v[148:151], v[180:183], v[128:131]
	v_mfma_f32_16x16x32_bf16 v[112:115], v[144:147], v[184:187], v[112:115]
	v_mfma_f32_16x16x32_bf16 v[112:115], v[148:151], v[188:191], v[112:115]
	v_mfma_f32_16x16x32_bf16 v[96:99], v[144:147], v[192:195], v[96:99]
	v_mfma_f32_16x16x32_bf16 v[96:99], v[148:151], v[196:199], v[96:99]
	v_mfma_f32_16x16x32_bf16 v[80:83], v[144:147], v[200:203], v[80:83]
	v_mfma_f32_16x16x32_bf16 v[80:83], v[148:151], v[204:207], v[80:83]
	v_mfma_f32_16x16x32_bf16 v[76:79], v[152:155], v[200:203], v[76:79]
	v_mfma_f32_16x16x32_bf16 v[76:79], v[156:159], v[204:207], v[76:79]
	v_mfma_f32_16x16x32_bf16 v[92:95], v[152:155], v[192:195], v[92:95]
	v_mfma_f32_16x16x32_bf16 v[92:95], v[156:159], v[196:199], v[92:95]
	v_mfma_f32_16x16x32_bf16 v[108:111], v[152:155], v[184:187], v[108:111]
	v_mfma_f32_16x16x32_bf16 v[108:111], v[156:159], v[188:191], v[108:111]
	v_mfma_f32_16x16x32_bf16 v[124:127], v[152:155], v[176:179], v[124:127]
	v_mfma_f32_16x16x32_bf16 v[124:127], v[156:159], v[180:183], v[124:127]

.Lt13b_2:
	s_barrier
	s_setprio 0
	s_mov_b32 m0, s24
	v_lshl_add_u64 v[208:209], v[208:209], 0, s[64:65]
	s_add_u32 s8, s8, 0x80080
	ds_read_b128 v[176:179], v143 offset:49152
	ds_read_b128 v[180:183], v143 offset:50176
	ds_read_b128 v[184:187], v143 offset:51200
	ds_read_b128 v[188:191], v143 offset:52224
	ds_read_b128 v[192:195], v143 offset:53248
	ds_read_b128 v[196:199], v143 offset:54272
	ds_read_b128 v[200:203], v143 offset:55296
	ds_read_b128 v[204:207], v143 offset:56320
	global_load_lds_dwordx4 v[208:209], off
	v_lshl_add_u64 v[208:209], v[210:211], 0, s[64:65]
	s_mov_b32 m0, s25
	s_addc_u32 s9, s9, 0
	global_load_lds_dwordx4 v[208:209], off
	v_lshl_add_u64 v[208:209], s[8:9], 0, v[2:3]
	s_mov_b32 m0, s34
	s_nop 0
	global_load_lds_dwordx4 v[208:209], off
	v_lshl_add_u64 v[208:209], s[8:9], 0, v[136:137]
	s_mov_b32 m0, s35
	s_nop 0
	global_load_lds_dwordx4 v[208:209], off
	v_lshl_add_u64 v[208:209], v[216:217], 0, s[64:65]
	s_mov_b32 m0, s26
	s_nop 0
	global_load_lds_dwordx4 v[208:209], off
	v_lshl_add_u64 v[208:209], v[218:219], 0, s[64:65]
	s_mov_b32 m0, s27
	s_nop 0
	global_load_lds_dwordx4 v[208:209], off
	s_waitcnt vmcnt(8)
	s_waitcnt lgkmcnt(0)
	s_setprio 1
	s_barrier
	s_cmp_lg_u32 s101, 0
	s_cbranch_scc1 .Lt13a_3
	v_mfma_f32_16x16x32_bf16 v[64:67], v[144:147], v[176:179], v[64:67]
	v_mfma_f32_16x16x32_bf16 v[64:67], v[148:151], v[180:183], v[64:67]
	v_mfma_f32_16x16x32_bf16 v[48:51], v[144:147], v[184:187], v[48:51]
	v_mfma_f32_16x16x32_bf16 v[48:51], v[148:151], v[188:191], v[48:51]
	v_mfma_f32_16x16x32_bf16 v[32:35], v[144:147], v[192:195], v[32:35]
	v_mfma_f32_16x16x32_bf16 v[32:35], v[148:151], v[196:199], v[32:35]
	v_mfma_f32_16x16x32_bf16 v[16:19], v[144:147], v[200:203], v[16:19]
	v_mfma_f32_16x16x32_bf16 v[16:19], v[148:151], v[204:207], v[16:19]
	v_mfma_f32_16x16x32_bf16 v[12:15], v[152:155], v[200:203], v[12:15]
	v_mfma_f32_16x16x32_bf16 v[12:15], v[156:159], v[204:207], v[12:15]
	v_mfma_f32_16x16x32_bf16 v[28:31], v[152:155], v[192:195], v[28:31]
	v_mfma_f32_16x16x32_bf16 v[28:31], v[156:159], v[196:199], v[28:31]
	v_mfma_f32_16x16x32_bf16 v[44:47], v[152:155], v[184:187], v[44:47]
	v_mfma_f32_16x16x32_bf16 v[44:47], v[156:159], v[188:191], v[44:47]
	v_mfma_f32_16x16x32_bf16 v[60:63], v[152:155], v[176:179], v[60:63]
	v_mfma_f32_16x16x32_bf16 v[60:63], v[156:159], v[180:183], v[60:63]

.Lt13b_3:
	s_barrier
	s_setprio 0
	s_add_i32 s43, s43, 2
	s_add_u32 s6, s6, 0x100
	s_addc_u32 s7, s7, 0
	s_cmp_gt_u32 s43, 29
	s_cbranch_scc0 .LBB0_1516
	s_cmpk_lt_u32 s21, 0x100
	s_cbranch_scc0 .LBB0_1519
	s_barrier

.LBB0_1876:
	v_add_u32_e32 v2, s83, v144
	ds_read_b128 v[146:149], v2
	ds_read_b128 v[150:153], v2 offset:1024
	ds_read_b128 v[154:157], v2 offset:2048
	ds_read_b128 v[158:161], v2 offset:3072
	v_add_u32_e32 v2, s44, v144
	ds_read_b128 v[162:165], v2
	ds_read_b128 v[166:169], v2 offset:1024
	ds_read_b128 v[170:173], v2 offset:2048
	ds_read_b128 v[174:177], v2 offset:3072
	s_add_i32 s70, s18, 2
	s_add_u32 s71, s42, 0x80
	s_addc_u32 s19, s43, 0
	s_cmp_eq_u32 s57, s18
	s_cselect_b32 s18, s34, s71
	s_cselect_b32 s19, s35, s19
	s_cselect_b32 s77, s25, s69
	s_cselect_b32 s76, s24, s68
	v_lshl_add_u64 v[210:211], s[42:43], 0, v[140:141]
	s_add_i32 m0, s23, 0xc000
	ds_read_b128 v[178:181], v145
	ds_read_b128 v[182:185], v145 offset:1024
	ds_read_b128 v[186:189], v145 offset:2048
	ds_read_b128 v[190:193], v145 offset:3072
	ds_read_b128 v[194:197], v145 offset:4096
	ds_read_b128 v[198:201], v145 offset:5120
	ds_read_b128 v[202:205], v145 offset:6144
	ds_read_b128 v[206:209], v145 offset:7168
	global_load_lds_dwordx4 v[210:211], off
	v_lshl_add_u64 v[210:211], s[42:43], 0, v[142:143]
	s_add_i32 m0, s23, 0xe000
	s_nop 0
	global_load_lds_dwordx4 v[210:211], off
	s_waitcnt vmcnt(8)
	s_waitcnt lgkmcnt(0)
	s_setprio 1
	s_barrier
	v_mfma_f32_16x16x32_bf16 v[120:123], v[146:149], v[178:181], v[120:123]
	v_mfma_f32_16x16x32_bf16 v[120:123], v[150:153], v[182:185], v[120:123]
	v_mfma_f32_16x16x32_bf16 v[112:115], v[146:149], v[186:189], v[112:115]
	v_mfma_f32_16x16x32_bf16 v[112:115], v[150:153], v[190:193], v[112:115]
	v_mfma_f32_16x16x32_bf16 v[96:99], v[146:149], v[194:197], v[96:99]
	v_mfma_f32_16x16x32_bf16 v[96:99], v[150:153], v[198:201], v[96:99]
	v_mfma_f32_16x16x32_bf16 v[80:83], v[146:149], v[202:205], v[80:83]
	v_mfma_f32_16x16x32_bf16 v[80:83], v[150:153], v[206:209], v[80:83]
	v_mfma_f32_16x16x32_bf16 v[76:79], v[154:157], v[202:205], v[76:79]
	v_mfma_f32_16x16x32_bf16 v[76:79], v[158:161], v[206:209], v[76:79]
	v_mfma_f32_16x16x32_bf16 v[92:95], v[154:157], v[194:197], v[92:95]
	v_mfma_f32_16x16x32_bf16 v[92:95], v[158:161], v[198:201], v[92:95]
	v_mfma_f32_16x16x32_bf16 v[108:111], v[154:157], v[186:189], v[108:111]
	v_mfma_f32_16x16x32_bf16 v[108:111], v[158:161], v[190:193], v[108:111]
	v_mfma_f32_16x16x32_bf16 v[128:131], v[154:157], v[178:181], v[128:131]
	v_mfma_f32_16x16x32_bf16 v[128:131], v[158:161], v[182:185], v[128:131]
	s_setprio 0
	s_setprio 1
	v_mfma_f32_16x16x32_bf16 v[124:127], v[162:165], v[178:181], v[124:127]
	v_mfma_f32_16x16x32_bf16 v[124:127], v[166:169], v[182:185], v[124:127]
	v_mfma_f32_16x16x32_bf16 v[104:107], v[162:165], v[186:189], v[104:107]
	v_mfma_f32_16x16x32_bf16 v[104:107], v[166:169], v[190:193], v[104:107]
	v_mfma_f32_16x16x32_bf16 v[88:91], v[162:165], v[194:197], v[88:91]
	v_mfma_f32_16x16x32_bf16 v[88:91], v[166:169], v[198:201], v[88:91]
	v_mfma_f32_16x16x32_bf16 v[72:75], v[162:165], v[202:205], v[72:75]
	v_mfma_f32_16x16x32_bf16 v[72:75], v[166:169], v[206:209], v[72:75]
	v_mfma_f32_16x16x32_bf16 v[68:71], v[170:173], v[202:205], v[68:71]
	v_mfma_f32_16x16x32_bf16 v[68:71], v[174:177], v[206:209], v[68:71]
	v_mfma_f32_16x16x32_bf16 v[84:87], v[170:173], v[194:197], v[84:87]
	v_mfma_f32_16x16x32_bf16 v[84:87], v[174:177], v[198:201], v[84:87]
	v_mfma_f32_16x16x32_bf16 v[100:103], v[170:173], v[186:189], v[100:103]
	v_mfma_f32_16x16x32_bf16 v[100:103], v[174:177], v[190:193], v[100:103]
	v_mfma_f32_16x16x32_bf16 v[116:119], v[170:173], v[178:181], v[116:119]
	v_mfma_f32_16x16x32_bf16 v[116:119], v[174:177], v[182:185], v[116:119]
	s_barrier
	s_setprio 0
	s_mov_b32 m0, s16
	v_lshl_add_u64 v[210:211], s[76:77], 0, v[134:135]
	v_lshl_add_u64 v[216:217], s[76:77], 0, v[138:139]
	s_add_u32 s76, s76, s4
	ds_read_b128 v[178:181], v145 offset:16384
	ds_read_b128 v[182:185], v145 offset:17408
	ds_read_b128 v[186:189], v145 offset:18432
	ds_read_b128 v[190:193], v145 offset:19456
	ds_read_b128 v[194:197], v145 offset:20480
	ds_read_b128 v[198:201], v145 offset:21504
	ds_read_b128 v[202:205], v145 offset:22528
	ds_read_b128 v[206:209], v145 offset:23552
	global_load_lds_dwordx4 v[210:211], off
	s_mov_b32 m0, s20
	s_addc_u32 s77, s77, s5
	global_load_lds_dwordx4 v[216:217], off
	v_lshl_add_u64 v[218:219], s[76:77], 0, v[134:135]
	s_mov_b32 m0, s21
	v_lshl_add_u64 v[220:221], s[76:77], 0, v[138:139]
	global_load_lds_dwordx4 v[218:219], off
	s_mov_b32 m0, s22
	v_lshl_add_u64 v[222:223], s[18:19], 0, v[132:133]
	global_load_lds_dwordx4 v[220:221], off
	s_mov_b32 m0, s23
	v_lshl_add_u64 v[224:225], s[18:19], 0, v[136:137]
	global_load_lds_dwordx4 v[222:223], off
	s_mov_b32 m0, s26
	s_nop 0
	global_load_lds_dwordx4 v[224:225], off
	s_waitcnt vmcnt(8)
	s_waitcnt lgkmcnt(0)
	s_setprio 1
	s_barrier
	v_mfma_f32_16x16x32_bf16 v[64:67], v[146:149], v[178:181], v[64:67]
	v_mfma_f32_16x16x32_bf16 v[64:67], v[150:153], v[182:185], v[64:67]
	v_mfma_f32_16x16x32_bf16 v[48:51], v[146:149], v[186:189], v[48:51]
	v_mfma_f32_16x16x32_bf16 v[48:51], v[150:153], v[190:193], v[48:51]
	v_mfma_f32_16x16x32_bf16 v[32:35], v[146:149], v[194:197], v[32:35]
	v_mfma_f32_16x16x32_bf16 v[32:35], v[150:153], v[198:201], v[32:35]
	v_mfma_f32_16x16x32_bf16 v[16:19], v[146:149], v[202:205], v[16:19]
	v_mfma_f32_16x16x32_bf16 v[16:19], v[150:153], v[206:209], v[16:19]
	v_mfma_f32_16x16x32_bf16 v[12:15], v[154:157], v[202:205], v[12:15]
	v_mfma_f32_16x16x32_bf16 v[12:15], v[158:161], v[206:209], v[12:15]
	v_mfma_f32_16x16x32_bf16 v[28:31], v[154:157], v[194:197], v[28:31]
	v_mfma_f32_16x16x32_bf16 v[28:31], v[158:161], v[198:201], v[28:31]
	v_mfma_f32_16x16x32_bf16 v[44:47], v[154:157], v[186:189], v[44:47]
	v_mfma_f32_16x16x32_bf16 v[44:47], v[158:161], v[190:193], v[44:47]
	v_mfma_f32_16x16x32_bf16 v[60:63], v[154:157], v[178:181], v[60:63]
	v_mfma_f32_16x16x32_bf16 v[60:63], v[158:161], v[182:185], v[60:63]
	s_setprio 0
	s_setprio 1
	v_mfma_f32_16x16x32_bf16 v[56:59], v[162:165], v[178:181], v[56:59]
	v_mfma_f32_16x16x32_bf16 v[56:59], v[166:169], v[182:185], v[56:59]
	v_mfma_f32_16x16x32_bf16 v[40:43], v[162:165], v[186:189], v[40:43]
	v_mfma_f32_16x16x32_bf16 v[40:43], v[166:169], v[190:193], v[40:43]
	v_mfma_f32_16x16x32_bf16 v[24:27], v[162:165], v[194:197], v[24:27]
	v_mfma_f32_16x16x32_bf16 v[24:27], v[166:169], v[198:201], v[24:27]
	v_mfma_f32_16x16x32_bf16 v[8:11], v[162:165], v[202:205], v[8:11]
	v_mfma_f32_16x16x32_bf16 v[8:11], v[166:169], v[206:209], v[8:11]
	v_mfma_f32_16x16x32_bf16 v[4:7], v[170:173], v[202:205], v[4:7]
	v_mfma_f32_16x16x32_bf16 v[4:7], v[174:177], v[206:209], v[4:7]
	v_mfma_f32_16x16x32_bf16 v[20:23], v[170:173], v[194:197], v[20:23]
	v_mfma_f32_16x16x32_bf16 v[20:23], v[174:177], v[198:201], v[20:23]
	v_mfma_f32_16x16x32_bf16 v[36:39], v[170:173], v[186:189], v[36:39]
	v_mfma_f32_16x16x32_bf16 v[36:39], v[174:177], v[190:193], v[36:39]
	v_mfma_f32_16x16x32_bf16 v[52:55], v[170:173], v[178:181], v[52:55]
	v_mfma_f32_16x16x32_bf16 v[52:55], v[174:177], v[182:185], v[52:55]
	s_barrier
	s_setprio 0
	v_add_u32_e32 v2, s45, v144
	ds_read_b128 v[146:149], v2
	ds_read_b128 v[150:153], v2 offset:1024
	ds_read_b128 v[154:157], v2 offset:2048
	ds_read_b128 v[158:161], v2 offset:3072
	v_add_u32_e32 v2, s74, v144
	ds_read_b128 v[162:165], v2
	ds_read_b128 v[166:169], v2 offset:1024
	ds_read_b128 v[170:173], v2 offset:2048
	ds_read_b128 v[174:177], v2 offset:3072
	s_add_u32 s18, s18, s4
	s_addc_u32 s19, s19, s5
	s_mov_b32 m0, s27
	v_lshl_add_u64 v[226:227], s[18:19], 0, v[132:133]
	ds_read_b128 v[178:181], v145 offset:32768
	ds_read_b128 v[182:185], v145 offset:33792
	ds_read_b128 v[186:189], v145 offset:34816
	ds_read_b128 v[190:193], v145 offset:35840
	ds_read_b128 v[194:197], v145 offset:36864
	ds_read_b128 v[198:201], v145 offset:37888
	ds_read_b128 v[202:205], v145 offset:38912
	ds_read_b128 v[206:209], v145 offset:39936
	global_load_lds_dwordx4 v[226:227], off
	v_lshl_add_u64 v[226:227], s[18:19], 0, v[136:137]
	s_mov_b32 m0, s37
	s_nop 0
	global_load_lds_dwordx4 v[226:227], off
	s_waitcnt vmcnt(8)
	s_waitcnt lgkmcnt(0)
	s_setprio 1
	s_barrier
	v_mfma_f32_16x16x32_bf16 v[120:123], v[146:149], v[178:181], v[120:123]
	v_mfma_f32_16x16x32_bf16 v[120:123], v[150:153], v[182:185], v[120:123]
	v_mfma_f32_16x16x32_bf16 v[112:115], v[146:149], v[186:189], v[112:115]
	v_mfma_f32_16x16x32_bf16 v[112:115], v[150:153], v[190:193], v[112:115]
	v_mfma_f32_16x16x32_bf16 v[96:99], v[146:149], v[194:197], v[96:99]
	v_mfma_f32_16x16x32_bf16 v[96:99], v[150:153], v[198:201], v[96:99]
	v_mfma_f32_16x16x32_bf16 v[80:83], v[146:149], v[202:205], v[80:83]
	v_mfma_f32_16x16x32_bf16 v[80:83], v[150:153], v[206:209], v[80:83]
	v_mfma_f32_16x16x32_bf16 v[76:79], v[154:157], v[202:205], v[76:79]
	v_mfma_f32_16x16x32_bf16 v[76:79], v[158:161], v[206:209], v[76:79]
	v_mfma_f32_16x16x32_bf16 v[92:95], v[154:157], v[194:197], v[92:95]
	v_mfma_f32_16x16x32_bf16 v[92:95], v[158:161], v[198:201], v[92:95]
	v_mfma_f32_16x16x32_bf16 v[108:111], v[154:157], v[186:189], v[108:111]
	v_mfma_f32_16x16x32_bf16 v[108:111], v[158:161], v[190:193], v[108:111]
	v_mfma_f32_16x16x32_bf16 v[128:131], v[154:157], v[178:181], v[128:131]
	v_mfma_f32_16x16x32_bf16 v[128:131], v[158:161], v[182:185], v[128:131]
	s_setprio 0
	s_setprio 1
	v_mfma_f32_16x16x32_bf16 v[124:127], v[162:165], v[178:181], v[124:127]
	v_mfma_f32_16x16x32_bf16 v[124:127], v[166:169], v[182:185], v[124:127]
	v_mfma_f32_16x16x32_bf16 v[104:107], v[162:165], v[186:189], v[104:107]
	v_mfma_f32_16x16x32_bf16 v[104:107], v[166:169], v[190:193], v[104:107]
	v_mfma_f32_16x16x32_bf16 v[88:91], v[162:165], v[194:197], v[88:91]
	v_mfma_f32_16x16x32_bf16 v[88:91], v[166:169], v[198:201], v[88:91]
	v_mfma_f32_16x16x32_bf16 v[72:75], v[162:165], v[202:205], v[72:75]
	v_mfma_f32_16x16x32_bf16 v[72:75], v[166:169], v[206:209], v[72:75]
	v_mfma_f32_16x16x32_bf16 v[68:71], v[170:173], v[202:205], v[68:71]
	v_mfma_f32_16x16x32_bf16 v[68:71], v[174:177], v[206:209], v[68:71]
	v_mfma_f32_16x16x32_bf16 v[84:87], v[170:173], v[194:197], v[84:87]
	v_mfma_f32_16x16x32_bf16 v[84:87], v[174:177], v[198:201], v[84:87]
	v_mfma_f32_16x16x32_bf16 v[100:103], v[170:173], v[186:189], v[100:103]
	v_mfma_f32_16x16x32_bf16 v[100:103], v[174:177], v[190:193], v[100:103]
	v_mfma_f32_16x16x32_bf16 v[116:119], v[170:173], v[178:181], v[116:119]
	v_mfma_f32_16x16x32_bf16 v[116:119], v[174:177], v[182:185], v[116:119]
	s_barrier
	s_setprio 0
	s_mov_b32 m0, s49
	v_lshl_add_u64 v[210:211], v[210:211], 0, s[64:65]
	ds_read_b128 v[178:181], v145 offset:49152
	ds_read_b128 v[182:185], v145 offset:50176
	ds_read_b128 v[186:189], v145 offset:51200
	ds_read_b128 v[190:193], v145 offset:52224
	ds_read_b128 v[194:197], v145 offset:53248
	ds_read_b128 v[198:201], v145 offset:54272
	ds_read_b128 v[202:205], v145 offset:55296
	ds_read_b128 v[206:209], v145 offset:56320
	global_load_lds_dwordx4 v[210:211], off
	v_lshl_add_u64 v[210:211], v[216:217], 0, s[64:65]
	s_mov_b32 m0, s50
	s_nop 0
	global_load_lds_dwordx4 v[210:211], off
	v_lshl_add_u64 v[210:211], v[218:219], 0, s[64:65]
	s_mov_b32 m0, s53
	s_nop 0
	global_load_lds_dwordx4 v[210:211], off
	v_lshl_add_u64 v[210:211], v[220:221], 0, s[64:65]
	s_mov_b32 m0, s56
	s_nop 0
	global_load_lds_dwordx4 v[210:211], off
	v_lshl_add_u64 v[210:211], v[222:223], 0, s[64:65]
	s_mov_b32 m0, s51
	s_nop 0
	global_load_lds_dwordx4 v[210:211], off
	v_lshl_add_u64 v[210:211], v[224:225], 0, s[64:65]
	s_mov_b32 m0, s52
	s_nop 0
	global_load_lds_dwordx4 v[210:211], off
	s_waitcnt vmcnt(8)
	s_waitcnt lgkmcnt(0)
	s_setprio 1
	s_barrier
	v_mfma_f32_16x16x32_bf16 v[64:67], v[146:149], v[178:181], v[64:67]
	v_mfma_f32_16x16x32_bf16 v[64:67], v[150:153], v[182:185], v[64:67]
	v_mfma_f32_16x16x32_bf16 v[48:51], v[146:149], v[186:189], v[48:51]
	v_mfma_f32_16x16x32_bf16 v[48:51], v[150:153], v[190:193], v[48:51]
	v_mfma_f32_16x16x32_bf16 v[32:35], v[146:149], v[194:197], v[32:35]
	v_mfma_f32_16x16x32_bf16 v[32:35], v[150:153], v[198:201], v[32:35]
	v_mfma_f32_16x16x32_bf16 v[16:19], v[146:149], v[202:205], v[16:19]
	v_mfma_f32_16x16x32_bf16 v[16:19], v[150:153], v[206:209], v[16:19]
	v_mfma_f32_16x16x32_bf16 v[12:15], v[154:157], v[202:205], v[12:15]
	v_mfma_f32_16x16x32_bf16 v[12:15], v[158:161], v[206:209], v[12:15]
	v_mfma_f32_16x16x32_bf16 v[28:31], v[154:157], v[194:197], v[28:31]
	v_mfma_f32_16x16x32_bf16 v[28:31], v[158:161], v[198:201], v[28:31]
	v_mfma_f32_16x16x32_bf16 v[44:47], v[154:157], v[186:189], v[44:47]
	v_mfma_f32_16x16x32_bf16 v[44:47], v[158:161], v[190:193], v[44:47]
	v_mfma_f32_16x16x32_bf16 v[60:63], v[154:157], v[178:181], v[60:63]
	v_mfma_f32_16x16x32_bf16 v[60:63], v[158:161], v[182:185], v[60:63]
	s_setprio 0
	s_setprio 1
	v_mfma_f32_16x16x32_bf16 v[56:59], v[162:165], v[178:181], v[56:59]
	v_mfma_f32_16x16x32_bf16 v[56:59], v[166:169], v[182:185], v[56:59]
	v_mfma_f32_16x16x32_bf16 v[40:43], v[162:165], v[186:189], v[40:43]
	v_mfma_f32_16x16x32_bf16 v[40:43], v[166:169], v[190:193], v[40:43]
	v_mfma_f32_16x16x32_bf16 v[24:27], v[162:165], v[194:197], v[24:27]
	v_mfma_f32_16x16x32_bf16 v[24:27], v[166:169], v[198:201], v[24:27]
	v_mfma_f32_16x16x32_bf16 v[8:11], v[162:165], v[202:205], v[8:11]
	v_mfma_f32_16x16x32_bf16 v[8:11], v[166:169], v[206:209], v[8:11]
	v_mfma_f32_16x16x32_bf16 v[4:7], v[170:173], v[202:205], v[4:7]
	v_mfma_f32_16x16x32_bf16 v[4:7], v[174:177], v[206:209], v[4:7]
	v_mfma_f32_16x16x32_bf16 v[20:23], v[170:173], v[194:197], v[20:23]
	v_mfma_f32_16x16x32_bf16 v[20:23], v[174:177], v[198:201], v[20:23]
	v_mfma_f32_16x16x32_bf16 v[36:39], v[170:173], v[186:189], v[36:39]
	v_mfma_f32_16x16x32_bf16 v[36:39], v[174:177], v[190:193], v[36:39]
	v_mfma_f32_16x16x32_bf16 v[52:55], v[170:173], v[178:181], v[52:55]
	v_mfma_f32_16x16x32_bf16 v[52:55], v[174:177], v[182:185], v[52:55]
	s_barrier
	s_setprio 0
	s_add_u32 s42, s42, 0x100
	s_addc_u32 s43, s43, 0
	s_add_u32 s68, s68, 0x100
	s_addc_u32 s69, s69, 0
	s_cmp_ge_i32 s70, s46
	s_mov_b32 s18, s70
	s_cbranch_scc0 .LBB0_1876

.LBB0_1891:
	v_add_u32_e32 v2, s83, v189
	ds_read_b128 v[28:31], v2
	ds_read_b128 v[32:35], v2 offset:16
	ds_read_b128 v[20:23], v2 offset:2048
	ds_read_b128 v[24:27], v2 offset:2064
	v_add_u32_e32 v2, s44, v189
	ds_read_b128 v[12:15], v2
	ds_read_b128 v[16:19], v2 offset:16
	ds_read_b128 v[4:7], v2 offset:2048
	ds_read_b128 v[8:11], v2 offset:2064
	s_add_u32 s10, s8, 0xfffc0080
	s_addc_u32 s11, s9, -1
	s_cmp_eq_u32 s25, 12
	s_cselect_b32 s13, s3, s11
	s_cselect_b32 s12, s14, s10
	s_cselect_b32 s11, s15, s24
	s_cselect_b32 s10, s18, s19
	v_lshl_add_u64 v[208:209], s[8:9], 0, v[172:173]
	s_add_i32 m0, s16, 0xc000
	ds_read_b128 v[176:179], v191
	ds_read_b128 v[180:183], v191 offset:16
	ds_read_b128 v[192:195], v191 offset:2048
	ds_read_b128 v[196:199], v191 offset:2064
	ds_read_b128 v[200:203], v191 offset:4096
	ds_read_b128 v[204:207], v191 offset:4112
	ds_read_b128 v[216:219], v191 offset:6144
	ds_read_b128 v[220:223], v191 offset:6160
	global_load_lds_dwordx4 v[208:209], off
	v_lshl_add_u64 v[208:209], s[8:9], 0, v[174:175]
	s_add_i32 m0, s16, 0xe000
	s_nop 0
	global_load_lds_dwordx4 v[208:209], off
	s_waitcnt vmcnt(8)
	s_waitcnt lgkmcnt(0)
	s_setprio 1
	s_barrier
	v_mfma_scale_f32_16x16x128_f8f6f4 v[160:163], v[28:35], v[176:183], v[160:163], v187, v185 op_sel_hi:[0,0,0]
	v_mfma_scale_f32_16x16x128_f8f6f4 v[156:159], v[20:27], v[176:183], v[156:159], v187, v185 op_sel_hi:[0,0,0]
	v_mfma_scale_f32_16x16x128_f8f6f4 v[144:147], v[28:35], v[192:199], v[144:147], v187, v185 op_sel_hi:[0,0,0]
	v_mfma_scale_f32_16x16x128_f8f6f4 v[140:143], v[20:27], v[192:199], v[140:143], v187, v185 op_sel_hi:[0,0,0]
	v_mfma_scale_f32_16x16x128_f8f6f4 v[128:131], v[28:35], v[200:207], v[128:131], v187, v185 op_sel_hi:[0,0,0]
	v_mfma_scale_f32_16x16x128_f8f6f4 v[124:127], v[20:27], v[200:207], v[124:127], v187, v185 op_sel_hi:[0,0,0]
	v_mfma_scale_f32_16x16x128_f8f6f4 v[112:115], v[28:35], v[216:223], v[112:115], v187, v185 op_sel_hi:[0,0,0]
	v_mfma_scale_f32_16x16x128_f8f6f4 v[108:111], v[20:27], v[216:223], v[108:111], v187, v185 op_sel_hi:[0,0,0]
	s_setprio 0
	s_setprio 1
	v_mfma_scale_f32_16x16x128_f8f6f4 v[152:155], v[12:19], v[176:183], v[152:155], v187, v185 op_sel_hi:[0,0,0]
	v_mfma_scale_f32_16x16x128_f8f6f4 v[148:151], v[4:11], v[176:183], v[148:151], v187, v185 op_sel_hi:[0,0,0]
	v_mfma_scale_f32_16x16x128_f8f6f4 v[136:139], v[12:19], v[192:199], v[136:139], v187, v185 op_sel_hi:[0,0,0]
	v_mfma_scale_f32_16x16x128_f8f6f4 v[132:135], v[4:11], v[192:199], v[132:135], v187, v185 op_sel_hi:[0,0,0]
	v_mfma_scale_f32_16x16x128_f8f6f4 v[120:123], v[12:19], v[200:207], v[120:123], v187, v185 op_sel_hi:[0,0,0]
	v_mfma_scale_f32_16x16x128_f8f6f4 v[116:119], v[4:11], v[200:207], v[116:119], v187, v185 op_sel_hi:[0,0,0]
	v_mfma_scale_f32_16x16x128_f8f6f4 v[104:107], v[12:19], v[216:223], v[104:107], v187, v185 op_sel_hi:[0,0,0]
	v_mfma_scale_f32_16x16x128_f8f6f4 v[100:103], v[4:11], v[216:223], v[100:103], v187, v185 op_sel_hi:[0,0,0]
	s_barrier
	s_setprio 0
	s_mov_b32 m0, s22
	v_lshl_add_u64 v[176:177], s[10:11], 0, v[166:167]
	s_add_u32 s56, s10, 0x40000
	ds_read_b128 v[192:195], v191 offset:16384
	ds_read_b128 v[196:199], v191 offset:16400
	ds_read_b128 v[200:203], v191 offset:18432
	ds_read_b128 v[204:207], v191 offset:18448
	ds_read_b128 v[216:219], v191 offset:20480
	ds_read_b128 v[220:223], v191 offset:20496
	ds_read_b128 v[224:227], v191 offset:22528
	ds_read_b128 v[228:231], v191 offset:22544
	global_load_lds_dwordx4 v[176:177], off
	v_lshl_add_u64 v[178:179], s[10:11], 0, v[170:171]
	s_mov_b32 m0, s23
	s_addc_u32 s57, s11, 0
	global_load_lds_dwordx4 v[178:179], off
	v_lshl_add_u64 v[180:181], s[56:57], 0, v[166:167]
	s_mov_b32 m0, s75
	v_lshl_add_u64 v[182:183], s[12:13], 0, v[168:169]
	global_load_lds_dwordx4 v[180:181], off
	v_lshl_add_u64 v[180:181], s[56:57], 0, v[170:171]
	s_mov_b32 m0, s37
	s_nop 0
	global_load_lds_dwordx4 v[180:181], off
	v_lshl_add_u64 v[180:181], s[12:13], 0, v[164:165]
	s_mov_b32 m0, s16
	s_nop 0
	global_load_lds_dwordx4 v[180:181], off
	s_mov_b32 m0, s73
	s_nop 0
	global_load_lds_dwordx4 v[182:183], off
	s_waitcnt vmcnt(8)
	s_waitcnt lgkmcnt(0)
	s_setprio 1
	s_barrier
	v_mfma_scale_f32_16x16x128_f8f6f4 v[96:99], v[28:35], v[192:199], v[96:99], v187, v185 op_sel_hi:[0,0,0]
	v_mfma_scale_f32_16x16x128_f8f6f4 v[92:95], v[20:27], v[192:199], v[92:95], v187, v185 op_sel_hi:[0,0,0]
	v_mfma_scale_f32_16x16x128_f8f6f4 v[80:83], v[28:35], v[200:207], v[80:83], v187, v185 op_sel_hi:[0,0,0]
	v_mfma_scale_f32_16x16x128_f8f6f4 v[76:79], v[20:27], v[200:207], v[76:79], v187, v185 op_sel_hi:[0,0,0]
	v_mfma_scale_f32_16x16x128_f8f6f4 v[64:67], v[28:35], v[216:223], v[64:67], v187, v185 op_sel_hi:[0,0,0]
	v_mfma_scale_f32_16x16x128_f8f6f4 v[60:63], v[20:27], v[216:223], v[60:63], v187, v185 op_sel_hi:[0,0,0]
	v_mfma_scale_f32_16x16x128_f8f6f4 v[48:51], v[28:35], v[224:231], v[48:51], v187, v185 op_sel_hi:[0,0,0]
	v_mfma_scale_f32_16x16x128_f8f6f4 v[44:47], v[20:27], v[224:231], v[44:47], v187, v185 op_sel_hi:[0,0,0]
	s_setprio 0
	s_setprio 1
	v_mfma_scale_f32_16x16x128_f8f6f4 v[88:91], v[12:19], v[192:199], v[88:91], v187, v185 op_sel_hi:[0,0,0]
	v_mfma_scale_f32_16x16x128_f8f6f4 v[84:87], v[4:11], v[192:199], v[84:87], v187, v185 op_sel_hi:[0,0,0]
	v_mfma_scale_f32_16x16x128_f8f6f4 v[72:75], v[12:19], v[200:207], v[72:75], v187, v185 op_sel_hi:[0,0,0]
	v_mfma_scale_f32_16x16x128_f8f6f4 v[68:71], v[4:11], v[200:207], v[68:71], v187, v185 op_sel_hi:[0,0,0]
	v_mfma_scale_f32_16x16x128_f8f6f4 v[56:59], v[12:19], v[216:223], v[56:59], v187, v185 op_sel_hi:[0,0,0]
	v_mfma_scale_f32_16x16x128_f8f6f4 v[52:55], v[4:11], v[216:223], v[52:55], v187, v185 op_sel_hi:[0,0,0]
	v_mfma_scale_f32_16x16x128_f8f6f4 v[40:43], v[12:19], v[224:231], v[40:43], v187, v185 op_sel_hi:[0,0,0]
	v_mfma_scale_f32_16x16x128_f8f6f4 v[36:39], v[4:11], v[224:231], v[36:39], v187, v185 op_sel_hi:[0,0,0]
	s_barrier
	s_setprio 0
	v_add_u32_e32 v2, s45, v189
	ds_read_b128 v[28:31], v2
	ds_read_b128 v[32:35], v2 offset:16
	ds_read_b128 v[20:23], v2 offset:2048
	ds_read_b128 v[24:27], v2 offset:2064
	v_add_u32_e32 v2, s74, v189
	ds_read_b128 v[12:15], v2
	ds_read_b128 v[16:19], v2 offset:16
	ds_read_b128 v[4:7], v2 offset:2048
	ds_read_b128 v[8:11], v2 offset:2064
	s_add_u32 s12, s12, 0x40000
	s_addc_u32 s13, s13, 0
	s_mov_b32 m0, s82
	v_lshl_add_u64 v[208:209], s[12:13], 0, v[164:165]
	ds_read_b128 v[192:195], v191 offset:32768
	ds_read_b128 v[196:199], v191 offset:32784
	ds_read_b128 v[200:203], v191 offset:34816
	ds_read_b128 v[204:207], v191 offset:34832
	ds_read_b128 v[216:219], v191 offset:36864
	ds_read_b128 v[220:223], v191 offset:36880
	ds_read_b128 v[224:227], v191 offset:38912
	ds_read_b128 v[228:231], v191 offset:38928
	global_load_lds_dwordx4 v[208:209], off
	v_lshl_add_u64 v[208:209], s[12:13], 0, v[168:169]
	s_mov_b32 m0, s40
	s_nop 0
	global_load_lds_dwordx4 v[208:209], off
	s_waitcnt vmcnt(8)
	s_waitcnt lgkmcnt(0)
	s_setprio 1
	s_barrier
	v_mfma_scale_f32_16x16x128_f8f6f4 v[160:163], v[28:35], v[192:199], v[160:163], v187, v185 op_sel_hi:[0,0,0]
	v_mfma_scale_f32_16x16x128_f8f6f4 v[156:159], v[20:27], v[192:199], v[156:159], v187, v185 op_sel_hi:[0,0,0]
	v_mfma_scale_f32_16x16x128_f8f6f4 v[144:147], v[28:35], v[200:207], v[144:147], v187, v185 op_sel_hi:[0,0,0]
	v_mfma_scale_f32_16x16x128_f8f6f4 v[140:143], v[20:27], v[200:207], v[140:143], v187, v185 op_sel_hi:[0,0,0]
	v_mfma_scale_f32_16x16x128_f8f6f4 v[128:131], v[28:35], v[216:223], v[128:131], v187, v185 op_sel_hi:[0,0,0]
	v_mfma_scale_f32_16x16x128_f8f6f4 v[124:127], v[20:27], v[216:223], v[124:127], v187, v185 op_sel_hi:[0,0,0]
	v_mfma_scale_f32_16x16x128_f8f6f4 v[112:115], v[28:35], v[224:231], v[112:115], v187, v185 op_sel_hi:[0,0,0]
	v_mfma_scale_f32_16x16x128_f8f6f4 v[108:111], v[20:27], v[224:231], v[108:111], v187, v185 op_sel_hi:[0,0,0]
	s_setprio 0
	s_setprio 1
	v_mfma_scale_f32_16x16x128_f8f6f4 v[152:155], v[12:19], v[192:199], v[152:155], v187, v185 op_sel_hi:[0,0,0]
	v_mfma_scale_f32_16x16x128_f8f6f4 v[148:151], v[4:11], v[192:199], v[148:151], v187, v185 op_sel_hi:[0,0,0]
	v_mfma_scale_f32_16x16x128_f8f6f4 v[136:139], v[12:19], v[200:207], v[136:139], v187, v185 op_sel_hi:[0,0,0]
	v_mfma_scale_f32_16x16x128_f8f6f4 v[132:135], v[4:11], v[200:207], v[132:135], v187, v185 op_sel_hi:[0,0,0]
	v_mfma_scale_f32_16x16x128_f8f6f4 v[120:123], v[12:19], v[216:223], v[120:123], v187, v185 op_sel_hi:[0,0,0]
	v_mfma_scale_f32_16x16x128_f8f6f4 v[116:119], v[4:11], v[216:223], v[116:119], v187, v185 op_sel_hi:[0,0,0]
	v_mfma_scale_f32_16x16x128_f8f6f4 v[104:107], v[12:19], v[224:231], v[104:107], v187, v185 op_sel_hi:[0,0,0]
	v_mfma_scale_f32_16x16x128_f8f6f4 v[100:103], v[4:11], v[224:231], v[100:103], v187, v185 op_sel_hi:[0,0,0]
	s_barrier
	s_setprio 0
	s_mov_b32 m0, s49
	v_lshl_add_u64 v[176:177], v[176:177], 0, s[64:65]
	s_add_u32 s10, s10, 0x40080
	ds_read_b128 v[192:195], v191 offset:49152
	ds_read_b128 v[196:199], v191 offset:49168
	ds_read_b128 v[200:203], v191 offset:51200
	ds_read_b128 v[204:207], v191 offset:51216
	ds_read_b128 v[216:219], v191 offset:53248
	ds_read_b128 v[220:223], v191 offset:53264
	ds_read_b128 v[224:227], v191 offset:55296
	ds_read_b128 v[228:231], v191 offset:55312
	global_load_lds_dwordx4 v[176:177], off
	v_lshl_add_u64 v[176:177], v[178:179], 0, s[64:65]
	s_mov_b32 m0, s84
	s_addc_u32 s11, s11, 0
	global_load_lds_dwordx4 v[176:177], off
	v_lshl_add_u64 v[176:177], s[10:11], 0, v[166:167]
	s_mov_b32 m0, s27
	s_nop 0
	global_load_lds_dwordx4 v[176:177], off
	v_lshl_add_u64 v[176:177], s[10:11], 0, v[170:171]
	s_mov_b32 m0, s48
	s_nop 0
	global_load_lds_dwordx4 v[176:177], off
	v_lshl_add_u64 v[176:177], v[180:181], 0, s[64:65]
	s_mov_b32 m0, s85
	s_nop 0
	global_load_lds_dwordx4 v[176:177], off
	v_lshl_add_u64 v[176:177], v[182:183], 0, s[64:65]
	s_mov_b32 m0, s26
	s_nop 0
	global_load_lds_dwordx4 v[176:177], off
	s_waitcnt vmcnt(8)
	s_waitcnt lgkmcnt(0)
	s_setprio 1
	s_barrier
	v_mfma_scale_f32_16x16x128_f8f6f4 v[96:99], v[28:35], v[192:199], v[96:99], v187, v185 op_sel_hi:[0,0,0]
	v_mfma_scale_f32_16x16x128_f8f6f4 v[92:95], v[20:27], v[192:199], v[92:95], v187, v185 op_sel_hi:[0,0,0]
	v_mfma_scale_f32_16x16x128_f8f6f4 v[80:83], v[28:35], v[200:207], v[80:83], v187, v185 op_sel_hi:[0,0,0]
	v_mfma_scale_f32_16x16x128_f8f6f4 v[76:79], v[20:27], v[200:207], v[76:79], v187, v185 op_sel_hi:[0,0,0]
	v_mfma_scale_f32_16x16x128_f8f6f4 v[64:67], v[28:35], v[216:223], v[64:67], v187, v185 op_sel_hi:[0,0,0]
	v_mfma_scale_f32_16x16x128_f8f6f4 v[60:63], v[20:27], v[216:223], v[60:63], v187, v185 op_sel_hi:[0,0,0]
	v_mfma_scale_f32_16x16x128_f8f6f4 v[48:51], v[28:35], v[224:231], v[48:51], v187, v185 op_sel_hi:[0,0,0]
	v_mfma_scale_f32_16x16x128_f8f6f4 v[44:47], v[20:27], v[224:231], v[44:47], v187, v185 op_sel_hi:[0,0,0]
	s_setprio 0
	s_setprio 1
	v_mfma_scale_f32_16x16x128_f8f6f4 v[88:91], v[12:19], v[192:199], v[88:91], v187, v185 op_sel_hi:[0,0,0]
	v_mfma_scale_f32_16x16x128_f8f6f4 v[84:87], v[4:11], v[192:199], v[84:87], v187, v185 op_sel_hi:[0,0,0]
	v_mfma_scale_f32_16x16x128_f8f6f4 v[72:75], v[12:19], v[200:207], v[72:75], v187, v185 op_sel_hi:[0,0,0]
	v_mfma_scale_f32_16x16x128_f8f6f4 v[68:71], v[4:11], v[200:207], v[68:71], v187, v185 op_sel_hi:[0,0,0]
	s_add_i32 s25, s25, 2
	v_mfma_scale_f32_16x16x128_f8f6f4 v[56:59], v[12:19], v[216:223], v[56:59], v187, v185 op_sel_hi:[0,0,0]
	s_add_u32 s8, s8, 0x100
	s_addc_u32 s9, s9, 0
	v_mfma_scale_f32_16x16x128_f8f6f4 v[52:55], v[4:11], v[216:223], v[52:55], v187, v185 op_sel_hi:[0,0,0]
	s_add_u32 s19, s19, 0x100
	s_addc_u32 s24, s24, 0
	v_mfma_scale_f32_16x16x128_f8f6f4 v[40:43], v[12:19], v[224:231], v[40:43], v187, v185 op_sel_hi:[0,0,0]
	s_cmp_gt_u32 s25, 13
	v_mfma_scale_f32_16x16x128_f8f6f4 v[36:39], v[4:11], v[224:231], v[36:39], v187, v185 op_sel_hi:[0,0,0]
	s_barrier
	s_setprio 0
	s_cbranch_scc0 .LBB0_1891
	v_readlane_b32 s8, v255, 13
	v_readlane_b32 s9, v255, 14
	s_and_b64 vcc, exec, s[8:9]
	s_cbranch_vccz .LBB0_1894
	s_barrier

.LBB0_2329:
	s_add_i32 s43, s12, 2
	v_add_u32_e32 v156, s83, v142
	v_add_u32_e32 v172, s44, v142
	s_add_u32 s10, s8, 0x100
	ds_read_b128 v[144:147], v156
	ds_read_b128 v[148:151], v156 offset:1024
	ds_read_b128 v[152:155], v156 offset:2048
	ds_read_b128 v[156:159], v156 offset:3072
	ds_read_b128 v[160:163], v172
	ds_read_b128 v[164:167], v172 offset:1024
	ds_read_b128 v[168:171], v172 offset:2048
	ds_read_b128 v[172:175], v172 offset:3072
	s_addc_u32 s11, s9, 0
	s_cmp_lg_u32 s42, s12
	s_cselect_b32 s46, s10, 0
	s_cselect_b32 s47, s11, 0
	s_add_u32 s12, s6, s46
	s_addc_u32 s13, s7, s47
	s_add_u32 s46, s4, s46
	s_addc_u32 s47, s5, s47
	v_lshl_add_u64 v[208:209], v[138:139], 0, s[8:9]
	s_add_i32 m0, s22, 0xc000
	ds_read_b128 v[176:179], v143
	ds_read_b128 v[180:183], v143 offset:1024
	ds_read_b128 v[184:187], v143 offset:2048
	ds_read_b128 v[188:191], v143 offset:3072
	ds_read_b128 v[192:195], v143 offset:4096
	ds_read_b128 v[196:199], v143 offset:5120
	ds_read_b128 v[200:203], v143 offset:6144
	ds_read_b128 v[204:207], v143 offset:7168
	global_load_lds_dwordx4 v[208:209], off
	v_lshl_add_u64 v[208:209], v[140:141], 0, s[8:9]
	s_add_i32 m0, s22, 0xe000
	s_nop 0
	global_load_lds_dwordx4 v[208:209], off
	s_waitcnt vmcnt(8)
	s_waitcnt lgkmcnt(0)
	s_setprio 1
	s_barrier
	v_mfma_f32_16x16x32_bf16 v[124:127], v[144:147], v[176:179], v[124:127]
	v_mfma_f32_16x16x32_bf16 v[124:127], v[148:151], v[180:183], v[124:127]
	v_mfma_f32_16x16x32_bf16 v[112:115], v[144:147], v[184:187], v[112:115]
	v_mfma_f32_16x16x32_bf16 v[112:115], v[148:151], v[188:191], v[112:115]
	v_mfma_f32_16x16x32_bf16 v[96:99], v[144:147], v[192:195], v[96:99]
	v_mfma_f32_16x16x32_bf16 v[96:99], v[148:151], v[196:199], v[96:99]
	v_mfma_f32_16x16x32_bf16 v[80:83], v[144:147], v[200:203], v[80:83]
	v_mfma_f32_16x16x32_bf16 v[80:83], v[148:151], v[204:207], v[80:83]
	v_mfma_f32_16x16x32_bf16 v[76:79], v[152:155], v[200:203], v[76:79]
	v_mfma_f32_16x16x32_bf16 v[76:79], v[156:159], v[204:207], v[76:79]
	v_mfma_f32_16x16x32_bf16 v[92:95], v[152:155], v[192:195], v[92:95]
	v_mfma_f32_16x16x32_bf16 v[92:95], v[156:159], v[196:199], v[92:95]
	v_mfma_f32_16x16x32_bf16 v[108:111], v[152:155], v[184:187], v[108:111]
	v_mfma_f32_16x16x32_bf16 v[108:111], v[156:159], v[188:191], v[108:111]
	v_mfma_f32_16x16x32_bf16 v[128:131], v[152:155], v[176:179], v[128:131]
	v_mfma_f32_16x16x32_bf16 v[128:131], v[156:159], v[180:183], v[128:131]
	s_setprio 0
	s_setprio 1
	v_mfma_f32_16x16x32_bf16 v[120:123], v[160:163], v[176:179], v[120:123]
	v_mfma_f32_16x16x32_bf16 v[120:123], v[164:167], v[180:183], v[120:123]
	v_mfma_f32_16x16x32_bf16 v[104:107], v[160:163], v[184:187], v[104:107]
	v_mfma_f32_16x16x32_bf16 v[104:107], v[164:167], v[188:191], v[104:107]
	v_mfma_f32_16x16x32_bf16 v[88:91], v[160:163], v[192:195], v[88:91]
	v_mfma_f32_16x16x32_bf16 v[88:91], v[164:167], v[196:199], v[88:91]
	v_mfma_f32_16x16x32_bf16 v[72:75], v[160:163], v[200:203], v[72:75]
	v_mfma_f32_16x16x32_bf16 v[72:75], v[164:167], v[204:207], v[72:75]
	v_mfma_f32_16x16x32_bf16 v[68:71], v[168:171], v[200:203], v[68:71]
	v_mfma_f32_16x16x32_bf16 v[68:71], v[172:175], v[204:207], v[68:71]
	v_mfma_f32_16x16x32_bf16 v[84:87], v[168:171], v[192:195], v[84:87]
	v_mfma_f32_16x16x32_bf16 v[84:87], v[172:175], v[196:199], v[84:87]
	v_mfma_f32_16x16x32_bf16 v[100:103], v[168:171], v[184:187], v[100:103]
	v_mfma_f32_16x16x32_bf16 v[100:103], v[172:175], v[188:191], v[100:103]
	v_mfma_f32_16x16x32_bf16 v[116:119], v[168:171], v[176:179], v[116:119]
	v_mfma_f32_16x16x32_bf16 v[116:119], v[172:175], v[180:183], v[116:119]
	s_barrier
	s_setprio 0
	s_mov_b32 m0, s18
	v_lshl_add_u64 v[208:209], s[46:47], 0, v[2:3]
	s_add_u32 s8, s46, s2
	ds_read_b128 v[176:179], v143 offset:16384
	ds_read_b128 v[180:183], v143 offset:17408
	ds_read_b128 v[184:187], v143 offset:18432
	ds_read_b128 v[188:191], v143 offset:19456
	ds_read_b128 v[192:195], v143 offset:20480
	ds_read_b128 v[196:199], v143 offset:21504
	ds_read_b128 v[200:203], v143 offset:22528
	ds_read_b128 v[204:207], v143 offset:23552
	global_load_lds_dwordx4 v[208:209], off
	v_lshl_add_u64 v[210:211], s[46:47], 0, v[136:137]
	s_mov_b32 m0, s19
	s_addc_u32 s9, s47, s3
	global_load_lds_dwordx4 v[210:211], off
	v_lshl_add_u64 v[216:217], s[8:9], 0, v[2:3]
	s_mov_b32 m0, s20
	v_lshl_add_u64 v[218:219], s[8:9], 0, v[136:137]
	global_load_lds_dwordx4 v[216:217], off
	s_mov_b32 m0, s21
	v_lshl_add_u64 v[220:221], s[12:13], 0, v[132:133]
	global_load_lds_dwordx4 v[218:219], off
	s_mov_b32 m0, s22
	v_lshl_add_u64 v[222:223], s[12:13], 0, v[134:135]
	global_load_lds_dwordx4 v[220:221], off
	s_mov_b32 m0, s23
	s_nop 0
	global_load_lds_dwordx4 v[222:223], off
	s_waitcnt vmcnt(8)
	s_waitcnt lgkmcnt(0)
	s_setprio 1
	s_barrier
	v_mfma_f32_16x16x32_bf16 v[64:67], v[144:147], v[176:179], v[64:67]
	v_mfma_f32_16x16x32_bf16 v[64:67], v[148:151], v[180:183], v[64:67]
	v_mfma_f32_16x16x32_bf16 v[48:51], v[144:147], v[184:187], v[48:51]
	v_mfma_f32_16x16x32_bf16 v[48:51], v[148:151], v[188:191], v[48:51]
	v_mfma_f32_16x16x32_bf16 v[32:35], v[144:147], v[192:195], v[32:35]
	v_mfma_f32_16x16x32_bf16 v[32:35], v[148:151], v[196:199], v[32:35]
	v_mfma_f32_16x16x32_bf16 v[16:19], v[144:147], v[200:203], v[16:19]
	v_mfma_f32_16x16x32_bf16 v[16:19], v[148:151], v[204:207], v[16:19]
	v_mfma_f32_16x16x32_bf16 v[12:15], v[152:155], v[200:203], v[12:15]
	v_mfma_f32_16x16x32_bf16 v[12:15], v[156:159], v[204:207], v[12:15]
	v_mfma_f32_16x16x32_bf16 v[28:31], v[152:155], v[192:195], v[28:31]
	v_mfma_f32_16x16x32_bf16 v[28:31], v[156:159], v[196:199], v[28:31]
	v_mfma_f32_16x16x32_bf16 v[44:47], v[152:155], v[184:187], v[44:47]
	v_mfma_f32_16x16x32_bf16 v[44:47], v[156:159], v[188:191], v[44:47]
	v_mfma_f32_16x16x32_bf16 v[60:63], v[152:155], v[176:179], v[60:63]
	v_mfma_f32_16x16x32_bf16 v[60:63], v[156:159], v[180:183], v[60:63]
	s_setprio 0
	s_setprio 1
	v_mfma_f32_16x16x32_bf16 v[56:59], v[160:163], v[176:179], v[56:59]
	v_mfma_f32_16x16x32_bf16 v[56:59], v[164:167], v[180:183], v[56:59]
	v_mfma_f32_16x16x32_bf16 v[40:43], v[160:163], v[184:187], v[40:43]
	v_mfma_f32_16x16x32_bf16 v[40:43], v[164:167], v[188:191], v[40:43]
	v_mfma_f32_16x16x32_bf16 v[24:27], v[160:163], v[192:195], v[24:27]
	v_mfma_f32_16x16x32_bf16 v[24:27], v[164:167], v[196:199], v[24:27]
	v_mfma_f32_16x16x32_bf16 v[8:11], v[160:163], v[200:203], v[8:11]
	v_mfma_f32_16x16x32_bf16 v[8:11], v[164:167], v[204:207], v[8:11]
	v_mfma_f32_16x16x32_bf16 v[4:7], v[168:171], v[200:203], v[4:7]
	v_mfma_f32_16x16x32_bf16 v[4:7], v[172:175], v[204:207], v[4:7]
	v_mfma_f32_16x16x32_bf16 v[20:23], v[168:171], v[192:195], v[20:23]
	v_mfma_f32_16x16x32_bf16 v[20:23], v[172:175], v[196:199], v[20:23]
	v_mfma_f32_16x16x32_bf16 v[36:39], v[168:171], v[184:187], v[36:39]
	v_mfma_f32_16x16x32_bf16 v[36:39], v[172:175], v[188:191], v[36:39]
	v_mfma_f32_16x16x32_bf16 v[52:55], v[168:171], v[176:179], v[52:55]
	v_mfma_f32_16x16x32_bf16 v[52:55], v[172:175], v[180:183], v[52:55]
	s_barrier
	s_setprio 0
	v_add_u32_e32 v156, s45, v142
	v_add_u32_e32 v172, s74, v142
	ds_read_b128 v[144:147], v156
	ds_read_b128 v[148:151], v156 offset:1024
	ds_read_b128 v[152:155], v156 offset:2048
	ds_read_b128 v[156:159], v156 offset:3072
	ds_read_b128 v[160:163], v172
	ds_read_b128 v[164:167], v172 offset:1024
	ds_read_b128 v[168:171], v172 offset:2048
	ds_read_b128 v[172:175], v172 offset:3072
	s_add_u32 s8, s12, s2
	s_addc_u32 s9, s13, s3
	s_mov_b32 m0, s24
	v_lshl_add_u64 v[224:225], s[8:9], 0, v[132:133]
	ds_read_b128 v[176:179], v143 offset:32768
	ds_read_b128 v[180:183], v143 offset:33792
	ds_read_b128 v[184:187], v143 offset:34816
	ds_read_b128 v[188:191], v143 offset:35840
	ds_read_b128 v[192:195], v143 offset:36864
	ds_read_b128 v[196:199], v143 offset:37888
	ds_read_b128 v[200:203], v143 offset:38912
	ds_read_b128 v[204:207], v143 offset:39936
	global_load_lds_dwordx4 v[224:225], off
	v_lshl_add_u64 v[224:225], s[8:9], 0, v[134:135]
	s_mov_b32 m0, s25
	s_nop 0
	global_load_lds_dwordx4 v[224:225], off
	s_waitcnt vmcnt(8)
	s_waitcnt lgkmcnt(0)
	s_setprio 1
	s_barrier
	v_mfma_f32_16x16x32_bf16 v[124:127], v[144:147], v[176:179], v[124:127]
	v_mfma_f32_16x16x32_bf16 v[124:127], v[148:151], v[180:183], v[124:127]
	v_mfma_f32_16x16x32_bf16 v[112:115], v[144:147], v[184:187], v[112:115]
	v_mfma_f32_16x16x32_bf16 v[112:115], v[148:151], v[188:191], v[112:115]
	v_mfma_f32_16x16x32_bf16 v[96:99], v[144:147], v[192:195], v[96:99]
	v_mfma_f32_16x16x32_bf16 v[96:99], v[148:151], v[196:199], v[96:99]
	v_mfma_f32_16x16x32_bf16 v[80:83], v[144:147], v[200:203], v[80:83]
	v_mfma_f32_16x16x32_bf16 v[80:83], v[148:151], v[204:207], v[80:83]
	v_mfma_f32_16x16x32_bf16 v[76:79], v[152:155], v[200:203], v[76:79]
	v_mfma_f32_16x16x32_bf16 v[76:79], v[156:159], v[204:207], v[76:79]
	v_mfma_f32_16x16x32_bf16 v[92:95], v[152:155], v[192:195], v[92:95]
	v_mfma_f32_16x16x32_bf16 v[92:95], v[156:159], v[196:199], v[92:95]
	v_mfma_f32_16x16x32_bf16 v[108:111], v[152:155], v[184:187], v[108:111]
	v_mfma_f32_16x16x32_bf16 v[108:111], v[156:159], v[188:191], v[108:111]
	v_mfma_f32_16x16x32_bf16 v[128:131], v[152:155], v[176:179], v[128:131]
	v_mfma_f32_16x16x32_bf16 v[128:131], v[156:159], v[180:183], v[128:131]
	s_setprio 0
	s_setprio 1
	v_mfma_f32_16x16x32_bf16 v[120:123], v[160:163], v[176:179], v[120:123]
	v_mfma_f32_16x16x32_bf16 v[120:123], v[164:167], v[180:183], v[120:123]
	v_mfma_f32_16x16x32_bf16 v[104:107], v[160:163], v[184:187], v[104:107]
	v_mfma_f32_16x16x32_bf16 v[104:107], v[164:167], v[188:191], v[104:107]
	v_mfma_f32_16x16x32_bf16 v[88:91], v[160:163], v[192:195], v[88:91]
	v_mfma_f32_16x16x32_bf16 v[88:91], v[164:167], v[196:199], v[88:91]
	v_mfma_f32_16x16x32_bf16 v[72:75], v[160:163], v[200:203], v[72:75]
	v_mfma_f32_16x16x32_bf16 v[72:75], v[164:167], v[204:207], v[72:75]
	v_mfma_f32_16x16x32_bf16 v[68:71], v[168:171], v[200:203], v[68:71]
	v_mfma_f32_16x16x32_bf16 v[68:71], v[172:175], v[204:207], v[68:71]
	v_mfma_f32_16x16x32_bf16 v[84:87], v[168:171], v[192:195], v[84:87]
	v_mfma_f32_16x16x32_bf16 v[84:87], v[172:175], v[196:199], v[84:87]
	v_mfma_f32_16x16x32_bf16 v[100:103], v[168:171], v[184:187], v[100:103]
	v_mfma_f32_16x16x32_bf16 v[100:103], v[172:175], v[188:191], v[100:103]
	v_mfma_f32_16x16x32_bf16 v[116:119], v[168:171], v[176:179], v[116:119]
	v_mfma_f32_16x16x32_bf16 v[116:119], v[172:175], v[180:183], v[116:119]
	s_barrier
	s_setprio 0
	s_mov_b32 m0, s26
	v_lshl_add_u64 v[208:209], v[208:209], 0, s[64:65]
	ds_read_b128 v[176:179], v143 offset:49152
	ds_read_b128 v[180:183], v143 offset:50176
	ds_read_b128 v[184:187], v143 offset:51200
	ds_read_b128 v[188:191], v143 offset:52224
	ds_read_b128 v[192:195], v143 offset:53248
	ds_read_b128 v[196:199], v143 offset:54272
	ds_read_b128 v[200:203], v143 offset:55296
	ds_read_b128 v[204:207], v143 offset:56320
	global_load_lds_dwordx4 v[208:209], off
	v_lshl_add_u64 v[208:209], v[210:211], 0, s[64:65]
	s_mov_b32 m0, s27
	s_nop 0
	global_load_lds_dwordx4 v[208:209], off
	v_lshl_add_u64 v[208:209], v[216:217], 0, s[64:65]
	s_mov_b32 m0, s37
	s_nop 0
	global_load_lds_dwordx4 v[208:209], off
	v_lshl_add_u64 v[208:209], v[218:219], 0, s[64:65]
	s_mov_b32 m0, s40
	s_nop 0
	global_load_lds_dwordx4 v[208:209], off
	v_lshl_add_u64 v[208:209], v[220:221], 0, s[64:65]
	s_mov_b32 m0, s34
	s_nop 0
	global_load_lds_dwordx4 v[208:209], off
	v_lshl_add_u64 v[208:209], v[222:223], 0, s[64:65]
	s_mov_b32 m0, s35
	s_nop 0
	global_load_lds_dwordx4 v[208:209], off
	s_waitcnt vmcnt(8)
	s_waitcnt lgkmcnt(0)
	s_setprio 1
	s_barrier
	v_mfma_f32_16x16x32_bf16 v[64:67], v[144:147], v[176:179], v[64:67]
	v_mfma_f32_16x16x32_bf16 v[64:67], v[148:151], v[180:183], v[64:67]
	v_mfma_f32_16x16x32_bf16 v[48:51], v[144:147], v[184:187], v[48:51]
	v_mfma_f32_16x16x32_bf16 v[48:51], v[148:151], v[188:191], v[48:51]
	v_mfma_f32_16x16x32_bf16 v[32:35], v[144:147], v[192:195], v[32:35]
	v_mfma_f32_16x16x32_bf16 v[32:35], v[148:151], v[196:199], v[32:35]
	v_mfma_f32_16x16x32_bf16 v[16:19], v[144:147], v[200:203], v[16:19]
	v_mfma_f32_16x16x32_bf16 v[16:19], v[148:151], v[204:207], v[16:19]
	v_mfma_f32_16x16x32_bf16 v[12:15], v[152:155], v[200:203], v[12:15]
	v_mfma_f32_16x16x32_bf16 v[12:15], v[156:159], v[204:207], v[12:15]
	v_mfma_f32_16x16x32_bf16 v[28:31], v[152:155], v[192:195], v[28:31]
	v_mfma_f32_16x16x32_bf16 v[28:31], v[156:159], v[196:199], v[28:31]
	v_mfma_f32_16x16x32_bf16 v[44:47], v[152:155], v[184:187], v[44:47]
	v_mfma_f32_16x16x32_bf16 v[44:47], v[156:159], v[188:191], v[44:47]
	v_mfma_f32_16x16x32_bf16 v[60:63], v[152:155], v[176:179], v[60:63]
	v_mfma_f32_16x16x32_bf16 v[60:63], v[156:159], v[180:183], v[60:63]
	s_setprio 0
	s_setprio 1
	v_mfma_f32_16x16x32_bf16 v[56:59], v[160:163], v[176:179], v[56:59]
	v_mfma_f32_16x16x32_bf16 v[56:59], v[164:167], v[180:183], v[56:59]
	v_mfma_f32_16x16x32_bf16 v[40:43], v[160:163], v[184:187], v[40:43]
	v_mfma_f32_16x16x32_bf16 v[40:43], v[164:167], v[188:191], v[40:43]
	v_mfma_f32_16x16x32_bf16 v[24:27], v[160:163], v[192:195], v[24:27]
	v_mfma_f32_16x16x32_bf16 v[24:27], v[164:167], v[196:199], v[24:27]
	v_mfma_f32_16x16x32_bf16 v[8:11], v[160:163], v[200:203], v[8:11]
	v_mfma_f32_16x16x32_bf16 v[8:11], v[164:167], v[204:207], v[8:11]
	v_mfma_f32_16x16x32_bf16 v[4:7], v[168:171], v[200:203], v[4:7]
	v_mfma_f32_16x16x32_bf16 v[4:7], v[172:175], v[204:207], v[4:7]
	v_mfma_f32_16x16x32_bf16 v[20:23], v[168:171], v[192:195], v[20:23]
	v_mfma_f32_16x16x32_bf16 v[20:23], v[172:175], v[196:199], v[20:23]
	v_mfma_f32_16x16x32_bf16 v[36:39], v[168:171], v[184:187], v[36:39]
	v_mfma_f32_16x16x32_bf16 v[36:39], v[172:175], v[188:191], v[36:39]
	v_mfma_f32_16x16x32_bf16 v[52:55], v[168:171], v[176:179], v[52:55]
	v_mfma_f32_16x16x32_bf16 v[52:55], v[172:175], v[180:183], v[52:55]
	s_barrier
	s_setprio 0
	s_cmp_ge_i32 s43, s41
	s_mov_b64 s[8:9], s[10:11]
	s_mov_b32 s12, s43
	s_cbranch_scc0 .LBB0_2329

.LBB0_2890:
	v_add_u32_e32 v4, s18, v184
	v_add_u32_e32 v8, s19, v184
	s_add_u32 s14, s48, s12
	ds_read_b128 v[28:31], v4
	ds_read_b128 v[32:35], v4 offset:16
	ds_read_b128 v[20:23], v4 offset:2048
	ds_read_b128 v[24:27], v4 offset:2064
	ds_read_b128 v[12:15], v8
	ds_read_b128 v[16:19], v8 offset:16
	ds_read_b128 v[4:7], v8 offset:2048
	ds_read_b128 v[8:11], v8 offset:2064
	s_addc_u32 s15, s49, s13
	s_add_u32 s14, s14, 0x45c00100
	s_addc_u32 s15, s15, 0
	s_add_u32 s53, s50, s12
	s_addc_u32 s56, s51, s13
	s_cmpk_eq_i32 s12, 0x700
	s_cselect_b32 s25, s11, s15
	s_cselect_b32 s24, s10, s14
	s_cselect_b32 s15, s3, s56
	s_cselect_b32 s14, s2, s53
	v_lshl_add_u64 v[210:211], v[170:171], 0, s[12:13]
	s_add_i32 m0, s37, 0xc000
	ds_read_b128 v[174:177], v185
	ds_read_b128 v[178:181], v185 offset:16
	ds_read_b128 v[186:189], v185 offset:2048
	ds_read_b128 v[190:193], v185 offset:2064
	ds_read_b128 v[194:197], v185 offset:4096
	ds_read_b128 v[198:201], v185 offset:4112
	ds_read_b128 v[202:205], v185 offset:6144
	ds_read_b128 v[206:209], v185 offset:6160
	global_load_lds_dwordx4 v[210:211], off
	v_lshl_add_u64 v[210:211], v[172:173], 0, s[12:13]
	s_add_i32 m0, s37, 0xe000
	s_nop 0
	global_load_lds_dwordx4 v[210:211], off
	s_waitcnt vmcnt(8)
	s_waitcnt lgkmcnt(0)
	s_setprio 1
	s_barrier
	v_mfma_scale_f32_16x16x128_f8f6f4 v[160:163], v[28:35], v[174:181], v[160:163], v183, v182 op_sel_hi:[0,0,0]
	v_mfma_scale_f32_16x16x128_f8f6f4 v[156:159], v[20:27], v[174:181], v[156:159], v183, v182 op_sel_hi:[0,0,0]
	v_mfma_scale_f32_16x16x128_f8f6f4 v[144:147], v[28:35], v[186:193], v[144:147], v183, v182 op_sel_hi:[0,0,0]
	v_mfma_scale_f32_16x16x128_f8f6f4 v[140:143], v[20:27], v[186:193], v[140:143], v183, v182 op_sel_hi:[0,0,0]
	v_mfma_scale_f32_16x16x128_f8f6f4 v[128:131], v[28:35], v[194:201], v[128:131], v183, v182 op_sel_hi:[0,0,0]
	v_mfma_scale_f32_16x16x128_f8f6f4 v[124:127], v[20:27], v[194:201], v[124:127], v183, v182 op_sel_hi:[0,0,0]
	v_mfma_scale_f32_16x16x128_f8f6f4 v[112:115], v[28:35], v[202:209], v[112:115], v183, v182 op_sel_hi:[0,0,0]
	v_mfma_scale_f32_16x16x128_f8f6f4 v[108:111], v[20:27], v[202:209], v[108:111], v183, v182 op_sel_hi:[0,0,0]
	s_setprio 0
	s_setprio 1
	v_mfma_scale_f32_16x16x128_f8f6f4 v[152:155], v[12:19], v[174:181], v[152:155], v183, v182 op_sel_hi:[0,0,0]
	v_mfma_scale_f32_16x16x128_f8f6f4 v[148:151], v[4:11], v[174:181], v[148:151], v183, v182 op_sel_hi:[0,0,0]
	v_mfma_scale_f32_16x16x128_f8f6f4 v[136:139], v[12:19], v[186:193], v[136:139], v183, v182 op_sel_hi:[0,0,0]
	v_mfma_scale_f32_16x16x128_f8f6f4 v[132:135], v[4:11], v[186:193], v[132:135], v183, v182 op_sel_hi:[0,0,0]
	v_mfma_scale_f32_16x16x128_f8f6f4 v[120:123], v[12:19], v[194:201], v[120:123], v183, v182 op_sel_hi:[0,0,0]
	v_mfma_scale_f32_16x16x128_f8f6f4 v[116:119], v[4:11], v[194:201], v[116:119], v183, v182 op_sel_hi:[0,0,0]
	v_mfma_scale_f32_16x16x128_f8f6f4 v[104:107], v[12:19], v[202:209], v[104:107], v183, v182 op_sel_hi:[0,0,0]
	v_mfma_scale_f32_16x16x128_f8f6f4 v[100:103], v[4:11], v[202:209], v[100:103], v183, v182 op_sel_hi:[0,0,0]
	s_barrier
	s_setprio 0
	s_mov_b32 m0, s23
	v_lshl_add_u64 v[174:175], s[14:15], 0, v[2:3]
	s_add_u32 s56, s14, 0x40000
	ds_read_b128 v[186:189], v185 offset:16384
	ds_read_b128 v[190:193], v185 offset:16400
	ds_read_b128 v[194:197], v185 offset:18432
	ds_read_b128 v[198:201], v185 offset:18448
	ds_read_b128 v[202:205], v185 offset:20480
	ds_read_b128 v[206:209], v185 offset:20496
	ds_read_b128 v[216:219], v185 offset:22528
	ds_read_b128 v[220:223], v185 offset:22544
	global_load_lds_dwordx4 v[174:175], off
	v_lshl_add_u64 v[176:177], s[14:15], 0, v[168:169]
	s_mov_b32 m0, s26
	s_addc_u32 s57, s15, 0
	global_load_lds_dwordx4 v[176:177], off
	v_lshl_add_u64 v[178:179], s[56:57], 0, v[2:3]
	s_mov_b32 m0, s27
	v_lshl_add_u64 v[180:181], s[24:25], 0, v[166:167]
	global_load_lds_dwordx4 v[178:179], off
	v_lshl_add_u64 v[178:179], s[56:57], 0, v[168:169]
	s_mov_b32 m0, s34
	s_nop 0
	global_load_lds_dwordx4 v[178:179], off
	v_lshl_add_u64 v[178:179], s[24:25], 0, v[164:165]
	s_mov_b32 m0, s37
	s_nop 0
	global_load_lds_dwordx4 v[178:179], off
	s_mov_b32 m0, s38
	s_nop 0
	global_load_lds_dwordx4 v[180:181], off
	s_waitcnt vmcnt(8)
	s_waitcnt lgkmcnt(0)
	s_setprio 1
	s_barrier
	v_mfma_scale_f32_16x16x128_f8f6f4 v[96:99], v[28:35], v[186:193], v[96:99], v183, v182 op_sel_hi:[0,0,0]
	v_mfma_scale_f32_16x16x128_f8f6f4 v[92:95], v[20:27], v[186:193], v[92:95], v183, v182 op_sel_hi:[0,0,0]
	v_mfma_scale_f32_16x16x128_f8f6f4 v[80:83], v[28:35], v[194:201], v[80:83], v183, v182 op_sel_hi:[0,0,0]
	v_mfma_scale_f32_16x16x128_f8f6f4 v[76:79], v[20:27], v[194:201], v[76:79], v183, v182 op_sel_hi:[0,0,0]
	v_mfma_scale_f32_16x16x128_f8f6f4 v[64:67], v[28:35], v[202:209], v[64:67], v183, v182 op_sel_hi:[0,0,0]
	v_mfma_scale_f32_16x16x128_f8f6f4 v[60:63], v[20:27], v[202:209], v[60:63], v183, v182 op_sel_hi:[0,0,0]
	v_mfma_scale_f32_16x16x128_f8f6f4 v[48:51], v[28:35], v[216:223], v[48:51], v183, v182 op_sel_hi:[0,0,0]
	v_mfma_scale_f32_16x16x128_f8f6f4 v[44:47], v[20:27], v[216:223], v[44:47], v183, v182 op_sel_hi:[0,0,0]
	s_setprio 0
	s_setprio 1
	v_mfma_scale_f32_16x16x128_f8f6f4 v[88:91], v[12:19], v[186:193], v[88:91], v183, v182 op_sel_hi:[0,0,0]
	v_mfma_scale_f32_16x16x128_f8f6f4 v[84:87], v[4:11], v[186:193], v[84:87], v183, v182 op_sel_hi:[0,0,0]
	v_mfma_scale_f32_16x16x128_f8f6f4 v[72:75], v[12:19], v[194:201], v[72:75], v183, v182 op_sel_hi:[0,0,0]
	v_mfma_scale_f32_16x16x128_f8f6f4 v[68:71], v[4:11], v[194:201], v[68:71], v183, v182 op_sel_hi:[0,0,0]
	v_mfma_scale_f32_16x16x128_f8f6f4 v[56:59], v[12:19], v[202:209], v[56:59], v183, v182 op_sel_hi:[0,0,0]
	v_mfma_scale_f32_16x16x128_f8f6f4 v[52:55], v[4:11], v[202:209], v[52:55], v183, v182 op_sel_hi:[0,0,0]
	v_mfma_scale_f32_16x16x128_f8f6f4 v[40:43], v[12:19], v[216:223], v[40:43], v183, v182 op_sel_hi:[0,0,0]
	v_mfma_scale_f32_16x16x128_f8f6f4 v[36:39], v[4:11], v[216:223], v[36:39], v183, v182 op_sel_hi:[0,0,0]
	s_barrier
	s_setprio 0
	v_add_u32_e32 v4, s20, v184
	v_add_u32_e32 v8, s21, v184
	ds_read_b128 v[28:31], v4
	ds_read_b128 v[32:35], v4 offset:16
	ds_read_b128 v[20:23], v4 offset:2048
	ds_read_b128 v[24:27], v4 offset:2064
	ds_read_b128 v[12:15], v8
	ds_read_b128 v[16:19], v8 offset:16
	ds_read_b128 v[4:7], v8 offset:2048
	ds_read_b128 v[8:11], v8 offset:2064
	s_add_u32 s24, s24, 0x40000
	s_addc_u32 s25, s25, 0
	s_mov_b32 m0, s39
	v_lshl_add_u64 v[210:211], s[24:25], 0, v[164:165]
	ds_read_b128 v[186:189], v185 offset:32768
	ds_read_b128 v[190:193], v185 offset:32784
	ds_read_b128 v[194:197], v185 offset:34816
	ds_read_b128 v[198:201], v185 offset:34832
	ds_read_b128 v[202:205], v185 offset:36864
	ds_read_b128 v[206:209], v185 offset:36880
	ds_read_b128 v[216:219], v185 offset:38912
	ds_read_b128 v[220:223], v185 offset:38928
	global_load_lds_dwordx4 v[210:211], off
	v_lshl_add_u64 v[210:211], s[24:25], 0, v[166:167]
	s_mov_b32 m0, s40
	s_nop 0
	global_load_lds_dwordx4 v[210:211], off
	s_waitcnt vmcnt(8)
	s_waitcnt lgkmcnt(0)
	s_setprio 1
	s_barrier
	v_mfma_scale_f32_16x16x128_f8f6f4 v[160:163], v[28:35], v[186:193], v[160:163], v183, v182 op_sel_hi:[0,0,0]
	v_mfma_scale_f32_16x16x128_f8f6f4 v[156:159], v[20:27], v[186:193], v[156:159], v183, v182 op_sel_hi:[0,0,0]
	v_mfma_scale_f32_16x16x128_f8f6f4 v[144:147], v[28:35], v[194:201], v[144:147], v183, v182 op_sel_hi:[0,0,0]
	v_mfma_scale_f32_16x16x128_f8f6f4 v[140:143], v[20:27], v[194:201], v[140:143], v183, v182 op_sel_hi:[0,0,0]
	v_mfma_scale_f32_16x16x128_f8f6f4 v[128:131], v[28:35], v[202:209], v[128:131], v183, v182 op_sel_hi:[0,0,0]
	v_mfma_scale_f32_16x16x128_f8f6f4 v[124:127], v[20:27], v[202:209], v[124:127], v183, v182 op_sel_hi:[0,0,0]
	v_mfma_scale_f32_16x16x128_f8f6f4 v[112:115], v[28:35], v[216:223], v[112:115], v183, v182 op_sel_hi:[0,0,0]
	v_mfma_scale_f32_16x16x128_f8f6f4 v[108:111], v[20:27], v[216:223], v[108:111], v183, v182 op_sel_hi:[0,0,0]
	s_setprio 0
	s_setprio 1
	v_mfma_scale_f32_16x16x128_f8f6f4 v[152:155], v[12:19], v[186:193], v[152:155], v183, v182 op_sel_hi:[0,0,0]
	v_mfma_scale_f32_16x16x128_f8f6f4 v[148:151], v[4:11], v[186:193], v[148:151], v183, v182 op_sel_hi:[0,0,0]
	v_mfma_scale_f32_16x16x128_f8f6f4 v[136:139], v[12:19], v[194:201], v[136:139], v183, v182 op_sel_hi:[0,0,0]
	v_mfma_scale_f32_16x16x128_f8f6f4 v[132:135], v[4:11], v[194:201], v[132:135], v183, v182 op_sel_hi:[0,0,0]
	v_mfma_scale_f32_16x16x128_f8f6f4 v[120:123], v[12:19], v[202:209], v[120:123], v183, v182 op_sel_hi:[0,0,0]
	v_mfma_scale_f32_16x16x128_f8f6f4 v[116:119], v[4:11], v[202:209], v[116:119], v183, v182 op_sel_hi:[0,0,0]
	v_mfma_scale_f32_16x16x128_f8f6f4 v[104:107], v[12:19], v[216:223], v[104:107], v183, v182 op_sel_hi:[0,0,0]
	v_mfma_scale_f32_16x16x128_f8f6f4 v[100:103], v[4:11], v[216:223], v[100:103], v183, v182 op_sel_hi:[0,0,0]
	s_barrier
	s_setprio 0
	s_mov_b32 m0, s42
	v_lshl_add_u64 v[174:175], v[174:175], 0, s[64:65]
	s_add_u32 s14, s14, 0x40080
	ds_read_b128 v[186:189], v185 offset:49152
	ds_read_b128 v[190:193], v185 offset:49168
	ds_read_b128 v[194:197], v185 offset:51200
	ds_read_b128 v[198:201], v185 offset:51216
	ds_read_b128 v[202:205], v185 offset:53248
	ds_read_b128 v[206:209], v185 offset:53264
	ds_read_b128 v[216:219], v185 offset:55296
	ds_read_b128 v[220:223], v185 offset:55312
	global_load_lds_dwordx4 v[174:175], off
	v_lshl_add_u64 v[174:175], v[176:177], 0, s[64:65]
	s_mov_b32 m0, s43
	s_addc_u32 s15, s15, 0
	global_load_lds_dwordx4 v[174:175], off
	v_lshl_add_u64 v[174:175], s[14:15], 0, v[2:3]
	s_mov_b32 m0, s46
	s_nop 0
	global_load_lds_dwordx4 v[174:175], off
	v_lshl_add_u64 v[174:175], s[14:15], 0, v[168:169]
	s_mov_b32 m0, s47
	s_nop 0
	global_load_lds_dwordx4 v[174:175], off
	v_lshl_add_u64 v[174:175], v[178:179], 0, s[64:65]
	s_mov_b32 m0, s44
	s_nop 0
	global_load_lds_dwordx4 v[174:175], off
	v_lshl_add_u64 v[174:175], v[180:181], 0, s[64:65]
	s_mov_b32 m0, s45
	s_nop 0
	global_load_lds_dwordx4 v[174:175], off
	s_waitcnt vmcnt(8)
	s_waitcnt lgkmcnt(0)
	s_setprio 1
	s_barrier
	v_mfma_scale_f32_16x16x128_f8f6f4 v[96:99], v[28:35], v[186:193], v[96:99], v183, v182 op_sel_hi:[0,0,0]
	v_mfma_scale_f32_16x16x128_f8f6f4 v[92:95], v[20:27], v[186:193], v[92:95], v183, v182 op_sel_hi:[0,0,0]
	v_mfma_scale_f32_16x16x128_f8f6f4 v[80:83], v[28:35], v[194:201], v[80:83], v183, v182 op_sel_hi:[0,0,0]
	v_mfma_scale_f32_16x16x128_f8f6f4 v[76:79], v[20:27], v[194:201], v[76:79], v183, v182 op_sel_hi:[0,0,0]
	v_mfma_scale_f32_16x16x128_f8f6f4 v[64:67], v[28:35], v[202:209], v[64:67], v183, v182 op_sel_hi:[0,0,0]
	v_mfma_scale_f32_16x16x128_f8f6f4 v[60:63], v[20:27], v[202:209], v[60:63], v183, v182 op_sel_hi:[0,0,0]
	v_mfma_scale_f32_16x16x128_f8f6f4 v[48:51], v[28:35], v[216:223], v[48:51], v183, v182 op_sel_hi:[0,0,0]
	v_mfma_scale_f32_16x16x128_f8f6f4 v[44:47], v[20:27], v[216:223], v[44:47], v183, v182 op_sel_hi:[0,0,0]
	s_setprio 0
	s_setprio 1
	v_mfma_scale_f32_16x16x128_f8f6f4 v[88:91], v[12:19], v[186:193], v[88:91], v183, v182 op_sel_hi:[0,0,0]
	v_mfma_scale_f32_16x16x128_f8f6f4 v[84:87], v[4:11], v[186:193], v[84:87], v183, v182 op_sel_hi:[0,0,0]
	v_mfma_scale_f32_16x16x128_f8f6f4 v[72:75], v[12:19], v[194:201], v[72:75], v183, v182 op_sel_hi:[0,0,0]
	v_mfma_scale_f32_16x16x128_f8f6f4 v[68:71], v[4:11], v[194:201], v[68:71], v183, v182 op_sel_hi:[0,0,0]
	s_add_i32 s52, s52, 2
	v_mfma_scale_f32_16x16x128_f8f6f4 v[56:59], v[12:19], v[202:209], v[56:59], v183, v182 op_sel_hi:[0,0,0]
	s_add_u32 s12, s12, 0x100
	s_addc_u32 s13, s13, 0
	v_mfma_scale_f32_16x16x128_f8f6f4 v[52:55], v[4:11], v[202:209], v[52:55], v183, v182 op_sel_hi:[0,0,0]
	s_cmp_gt_u32 s52, 13
	v_mfma_scale_f32_16x16x128_f8f6f4 v[40:43], v[12:19], v[216:223], v[40:43], v183, v182 op_sel_hi:[0,0,0]
	v_mfma_scale_f32_16x16x128_f8f6f4 v[36:39], v[4:11], v[216:223], v[36:39], v183, v182 op_sel_hi:[0,0,0]
	s_barrier
	s_setprio 0
	s_cbranch_scc0 .LBB0_2890
	s_cmpk_lt_u32 s22, 0x100
	s_cbranch_scc0 .LBB0_2893
	s_barrier

.LBB0_2896:
	v_add_u32_e32 v148, s18, v126
	v_add_u32_e32 v172, s19, v126
	s_add_u32 s12, s46, s8
	ds_read_b128 v[128:131], v148
	ds_read_b128 v[132:135], v148 offset:1024
	ds_read_b128 v[140:143], v148 offset:2048
	ds_read_b128 v[148:151], v148 offset:3072
	ds_read_b128 v[160:163], v172
	ds_read_b128 v[164:167], v172 offset:1024
	ds_read_b128 v[168:171], v172 offset:2048
	ds_read_b128 v[172:175], v172 offset:3072
	s_addc_u32 s13, s47, s9
	s_add_u32 s12, s12, 0x34400100
	s_addc_u32 s13, s13, 0
	s_add_u32 s16, s48, s8
	s_addc_u32 s51, s49, s9
	s_cmpk_eq_i32 s8, 0xf00
	s_cselect_b32 s15, s11, s13
	s_cselect_b32 s14, s10, s12
	s_cselect_b32 s13, s3, s51
	s_cselect_b32 s12, s2, s16
	v_lshl_add_u64 v[208:209], v[122:123], 0, s[8:9]
	s_add_i32 m0, s27, 0xc000
	ds_read_b128 v[176:179], v127
	ds_read_b128 v[180:183], v127 offset:1024
	ds_read_b128 v[184:187], v127 offset:2048
	ds_read_b128 v[188:191], v127 offset:3072
	ds_read_b128 v[192:195], v127 offset:4096
	ds_read_b128 v[196:199], v127 offset:5120
	ds_read_b128 v[200:203], v127 offset:6144
	ds_read_b128 v[204:207], v127 offset:7168
	global_load_lds_dwordx4 v[208:209], off
	v_lshl_add_u64 v[208:209], v[124:125], 0, s[8:9]
	s_add_i32 m0, s27, 0xe000
	s_nop 0
	global_load_lds_dwordx4 v[208:209], off
	s_waitcnt vmcnt(8)
	s_waitcnt lgkmcnt(0)
	s_setprio 1
	s_barrier
	v_mfma_f32_16x16x32_bf16 v[156:159], v[128:131], v[176:179], v[156:159]
	v_mfma_f32_16x16x32_bf16 v[156:159], v[132:135], v[180:183], v[156:159]
	v_mfma_f32_16x16x32_bf16 v[112:115], v[128:131], v[184:187], v[112:115]
	v_mfma_f32_16x16x32_bf16 v[112:115], v[132:135], v[188:191], v[112:115]
	v_mfma_f32_16x16x32_bf16 v[96:99], v[128:131], v[192:195], v[96:99]
	v_mfma_f32_16x16x32_bf16 v[96:99], v[132:135], v[196:199], v[96:99]
	v_mfma_f32_16x16x32_bf16 v[80:83], v[128:131], v[200:203], v[80:83]
	v_mfma_f32_16x16x32_bf16 v[80:83], v[132:135], v[204:207], v[80:83]
	v_mfma_f32_16x16x32_bf16 v[76:79], v[140:143], v[200:203], v[76:79]
	v_mfma_f32_16x16x32_bf16 v[76:79], v[148:151], v[204:207], v[76:79]
	v_mfma_f32_16x16x32_bf16 v[92:95], v[140:143], v[192:195], v[92:95]
	v_mfma_f32_16x16x32_bf16 v[92:95], v[148:151], v[196:199], v[92:95]
	v_mfma_f32_16x16x32_bf16 v[108:111], v[140:143], v[184:187], v[108:111]
	v_mfma_f32_16x16x32_bf16 v[108:111], v[148:151], v[188:191], v[108:111]
	v_mfma_f32_16x16x32_bf16 v[152:155], v[140:143], v[176:179], v[152:155]
	v_mfma_f32_16x16x32_bf16 v[152:155], v[148:151], v[180:183], v[152:155]
	s_setprio 0
	s_setprio 1
	v_mfma_f32_16x16x32_bf16 v[144:147], v[160:163], v[176:179], v[144:147]
	v_mfma_f32_16x16x32_bf16 v[144:147], v[164:167], v[180:183], v[144:147]
	v_mfma_f32_16x16x32_bf16 v[104:107], v[160:163], v[184:187], v[104:107]
	v_mfma_f32_16x16x32_bf16 v[104:107], v[164:167], v[188:191], v[104:107]
	v_mfma_f32_16x16x32_bf16 v[88:91], v[160:163], v[192:195], v[88:91]
	v_mfma_f32_16x16x32_bf16 v[88:91], v[164:167], v[196:199], v[88:91]
	v_mfma_f32_16x16x32_bf16 v[72:75], v[160:163], v[200:203], v[72:75]
	v_mfma_f32_16x16x32_bf16 v[72:75], v[164:167], v[204:207], v[72:75]
	v_mfma_f32_16x16x32_bf16 v[68:71], v[168:171], v[200:203], v[68:71]
	v_mfma_f32_16x16x32_bf16 v[68:71], v[172:175], v[204:207], v[68:71]
	v_mfma_f32_16x16x32_bf16 v[84:87], v[168:171], v[192:195], v[84:87]
	v_mfma_f32_16x16x32_bf16 v[84:87], v[172:175], v[196:199], v[84:87]
	v_mfma_f32_16x16x32_bf16 v[100:103], v[168:171], v[184:187], v[100:103]
	v_mfma_f32_16x16x32_bf16 v[100:103], v[172:175], v[188:191], v[100:103]
	v_mfma_f32_16x16x32_bf16 v[136:139], v[168:171], v[176:179], v[136:139]
	v_mfma_f32_16x16x32_bf16 v[136:139], v[172:175], v[180:183], v[136:139]
	s_barrier
	s_setprio 0
	s_mov_b32 m0, s23
	v_lshl_add_u64 v[208:209], s[12:13], 0, v[2:3]
	s_add_u32 s52, s12, 0x80000
	ds_read_b128 v[176:179], v127 offset:16384
	ds_read_b128 v[180:183], v127 offset:17408
	ds_read_b128 v[184:187], v127 offset:18432
	ds_read_b128 v[188:191], v127 offset:19456
	ds_read_b128 v[192:195], v127 offset:20480
	ds_read_b128 v[196:199], v127 offset:21504
	ds_read_b128 v[200:203], v127 offset:22528
	ds_read_b128 v[204:207], v127 offset:23552
	global_load_lds_dwordx4 v[208:209], off
	v_lshl_add_u64 v[210:211], s[12:13], 0, v[120:121]
	s_mov_b32 m0, s24
	s_addc_u32 s53, s13, 0
	global_load_lds_dwordx4 v[210:211], off
	v_lshl_add_u64 v[216:217], s[52:53], 0, v[2:3]
	s_mov_b32 m0, s25
	v_lshl_add_u64 v[218:219], s[14:15], 0, v[118:119]
	global_load_lds_dwordx4 v[216:217], off
	v_lshl_add_u64 v[216:217], s[52:53], 0, v[120:121]
	s_mov_b32 m0, s26
	s_nop 0
	global_load_lds_dwordx4 v[216:217], off
	v_lshl_add_u64 v[216:217], s[14:15], 0, v[116:117]
	s_mov_b32 m0, s27
	s_nop 0
	global_load_lds_dwordx4 v[216:217], off
	s_mov_b32 m0, s35
	s_nop 0
	global_load_lds_dwordx4 v[218:219], off
	s_waitcnt vmcnt(8)
	s_waitcnt lgkmcnt(0)
	s_setprio 1
	s_barrier
	v_mfma_f32_16x16x32_bf16 v[64:67], v[128:131], v[176:179], v[64:67]
	v_mfma_f32_16x16x32_bf16 v[64:67], v[132:135], v[180:183], v[64:67]
	v_mfma_f32_16x16x32_bf16 v[48:51], v[128:131], v[184:187], v[48:51]
	v_mfma_f32_16x16x32_bf16 v[48:51], v[132:135], v[188:191], v[48:51]
	v_mfma_f32_16x16x32_bf16 v[32:35], v[128:131], v[192:195], v[32:35]
	v_mfma_f32_16x16x32_bf16 v[32:35], v[132:135], v[196:199], v[32:35]
	v_mfma_f32_16x16x32_bf16 v[16:19], v[128:131], v[200:203], v[16:19]
	v_mfma_f32_16x16x32_bf16 v[16:19], v[132:135], v[204:207], v[16:19]
	v_mfma_f32_16x16x32_bf16 v[12:15], v[140:143], v[200:203], v[12:15]
	v_mfma_f32_16x16x32_bf16 v[12:15], v[148:151], v[204:207], v[12:15]
	v_mfma_f32_16x16x32_bf16 v[28:31], v[140:143], v[192:195], v[28:31]
	v_mfma_f32_16x16x32_bf16 v[28:31], v[148:151], v[196:199], v[28:31]
	v_mfma_f32_16x16x32_bf16 v[44:47], v[140:143], v[184:187], v[44:47]
	v_mfma_f32_16x16x32_bf16 v[44:47], v[148:151], v[188:191], v[44:47]
	v_mfma_f32_16x16x32_bf16 v[60:63], v[140:143], v[176:179], v[60:63]
	v_mfma_f32_16x16x32_bf16 v[60:63], v[148:151], v[180:183], v[60:63]
	s_setprio 0
	s_setprio 1
	v_mfma_f32_16x16x32_bf16 v[56:59], v[160:163], v[176:179], v[56:59]
	v_mfma_f32_16x16x32_bf16 v[56:59], v[164:167], v[180:183], v[56:59]
	v_mfma_f32_16x16x32_bf16 v[40:43], v[160:163], v[184:187], v[40:43]
	v_mfma_f32_16x16x32_bf16 v[40:43], v[164:167], v[188:191], v[40:43]
	v_mfma_f32_16x16x32_bf16 v[24:27], v[160:163], v[192:195], v[24:27]
	v_mfma_f32_16x16x32_bf16 v[24:27], v[164:167], v[196:199], v[24:27]
	v_mfma_f32_16x16x32_bf16 v[8:11], v[160:163], v[200:203], v[8:11]
	v_mfma_f32_16x16x32_bf16 v[8:11], v[164:167], v[204:207], v[8:11]
	v_mfma_f32_16x16x32_bf16 v[4:7], v[168:171], v[200:203], v[4:7]
	v_mfma_f32_16x16x32_bf16 v[4:7], v[172:175], v[204:207], v[4:7]
	v_mfma_f32_16x16x32_bf16 v[20:23], v[168:171], v[192:195], v[20:23]
	v_mfma_f32_16x16x32_bf16 v[20:23], v[172:175], v[196:199], v[20:23]
	v_mfma_f32_16x16x32_bf16 v[36:39], v[168:171], v[184:187], v[36:39]
	v_mfma_f32_16x16x32_bf16 v[36:39], v[172:175], v[188:191], v[36:39]
	v_mfma_f32_16x16x32_bf16 v[52:55], v[168:171], v[176:179], v[52:55]
	v_mfma_f32_16x16x32_bf16 v[52:55], v[172:175], v[180:183], v[52:55]
	s_barrier
	s_setprio 0
	v_add_u32_e32 v148, s20, v126
	v_add_u32_e32 v172, s21, v126
	ds_read_b128 v[128:131], v148
	ds_read_b128 v[132:135], v148 offset:1024
	ds_read_b128 v[140:143], v148 offset:2048
	ds_read_b128 v[148:151], v148 offset:3072
	ds_read_b128 v[160:163], v172
	ds_read_b128 v[164:167], v172 offset:1024
	ds_read_b128 v[168:171], v172 offset:2048
	ds_read_b128 v[172:175], v172 offset:3072
	s_add_u32 s14, s14, 0x80000
	s_addc_u32 s15, s15, 0
	s_mov_b32 m0, s37
	v_lshl_add_u64 v[220:221], s[14:15], 0, v[116:117]
	ds_read_b128 v[176:179], v127 offset:32768
	ds_read_b128 v[180:183], v127 offset:33792
	ds_read_b128 v[184:187], v127 offset:34816
	ds_read_b128 v[188:191], v127 offset:35840
	ds_read_b128 v[192:195], v127 offset:36864
	ds_read_b128 v[196:199], v127 offset:37888
	ds_read_b128 v[200:203], v127 offset:38912
	ds_read_b128 v[204:207], v127 offset:39936
	global_load_lds_dwordx4 v[220:221], off
	v_lshl_add_u64 v[220:221], s[14:15], 0, v[118:119]
	s_mov_b32 m0, s38
	s_nop 0
	global_load_lds_dwordx4 v[220:221], off
	s_waitcnt vmcnt(8)
	s_waitcnt lgkmcnt(0)
	s_setprio 1
	s_barrier
	v_mfma_f32_16x16x32_bf16 v[156:159], v[128:131], v[176:179], v[156:159]
	v_mfma_f32_16x16x32_bf16 v[156:159], v[132:135], v[180:183], v[156:159]
	v_mfma_f32_16x16x32_bf16 v[112:115], v[128:131], v[184:187], v[112:115]
	v_mfma_f32_16x16x32_bf16 v[112:115], v[132:135], v[188:191], v[112:115]
	v_mfma_f32_16x16x32_bf16 v[96:99], v[128:131], v[192:195], v[96:99]
	v_mfma_f32_16x16x32_bf16 v[96:99], v[132:135], v[196:199], v[96:99]
	v_mfma_f32_16x16x32_bf16 v[80:83], v[128:131], v[200:203], v[80:83]
	v_mfma_f32_16x16x32_bf16 v[80:83], v[132:135], v[204:207], v[80:83]
	v_mfma_f32_16x16x32_bf16 v[76:79], v[140:143], v[200:203], v[76:79]
	v_mfma_f32_16x16x32_bf16 v[76:79], v[148:151], v[204:207], v[76:79]
	v_mfma_f32_16x16x32_bf16 v[92:95], v[140:143], v[192:195], v[92:95]
	v_mfma_f32_16x16x32_bf16 v[92:95], v[148:151], v[196:199], v[92:95]
	v_mfma_f32_16x16x32_bf16 v[108:111], v[140:143], v[184:187], v[108:111]
	v_mfma_f32_16x16x32_bf16 v[108:111], v[148:151], v[188:191], v[108:111]
	v_mfma_f32_16x16x32_bf16 v[152:155], v[140:143], v[176:179], v[152:155]
	v_mfma_f32_16x16x32_bf16 v[152:155], v[148:151], v[180:183], v[152:155]
	s_setprio 0
	s_setprio 1
	v_mfma_f32_16x16x32_bf16 v[144:147], v[160:163], v[176:179], v[144:147]
	v_mfma_f32_16x16x32_bf16 v[144:147], v[164:167], v[180:183], v[144:147]
	v_mfma_f32_16x16x32_bf16 v[104:107], v[160:163], v[184:187], v[104:107]
	v_mfma_f32_16x16x32_bf16 v[104:107], v[164:167], v[188:191], v[104:107]
	v_mfma_f32_16x16x32_bf16 v[88:91], v[160:163], v[192:195], v[88:91]
	v_mfma_f32_16x16x32_bf16 v[88:91], v[164:167], v[196:199], v[88:91]
	v_mfma_f32_16x16x32_bf16 v[72:75], v[160:163], v[200:203], v[72:75]
	v_mfma_f32_16x16x32_bf16 v[72:75], v[164:167], v[204:207], v[72:75]
	v_mfma_f32_16x16x32_bf16 v[68:71], v[168:171], v[200:203], v[68:71]
	v_mfma_f32_16x16x32_bf16 v[68:71], v[172:175], v[204:207], v[68:71]
	v_mfma_f32_16x16x32_bf16 v[84:87], v[168:171], v[192:195], v[84:87]
	v_mfma_f32_16x16x32_bf16 v[84:87], v[172:175], v[196:199], v[84:87]
	v_mfma_f32_16x16x32_bf16 v[100:103], v[168:171], v[184:187], v[100:103]
	v_mfma_f32_16x16x32_bf16 v[100:103], v[172:175], v[188:191], v[100:103]
	v_mfma_f32_16x16x32_bf16 v[136:139], v[168:171], v[176:179], v[136:139]
	v_mfma_f32_16x16x32_bf16 v[136:139], v[172:175], v[180:183], v[136:139]
	s_barrier
	s_setprio 0
	s_mov_b32 m0, s40
	v_lshl_add_u64 v[208:209], v[208:209], 0, s[64:65]
	s_add_u32 s12, s12, 0x80080
	ds_read_b128 v[176:179], v127 offset:49152
	ds_read_b128 v[180:183], v127 offset:50176
	ds_read_b128 v[184:187], v127 offset:51200
	ds_read_b128 v[188:191], v127 offset:52224
	ds_read_b128 v[192:195], v127 offset:53248
	ds_read_b128 v[196:199], v127 offset:54272
	ds_read_b128 v[200:203], v127 offset:55296
	ds_read_b128 v[204:207], v127 offset:56320
	global_load_lds_dwordx4 v[208:209], off
	v_lshl_add_u64 v[208:209], v[210:211], 0, s[64:65]
	s_mov_b32 m0, s41
	s_addc_u32 s13, s13, 0
	global_load_lds_dwordx4 v[208:209], off
	v_lshl_add_u64 v[208:209], s[12:13], 0, v[2:3]
	s_mov_b32 m0, s44
	s_nop 0
	global_load_lds_dwordx4 v[208:209], off
	v_lshl_add_u64 v[208:209], s[12:13], 0, v[120:121]
	s_mov_b32 m0, s45
	s_nop 0
	global_load_lds_dwordx4 v[208:209], off
	v_lshl_add_u64 v[208:209], v[216:217], 0, s[64:65]
	s_mov_b32 m0, s42
	s_nop 0
	global_load_lds_dwordx4 v[208:209], off
	v_lshl_add_u64 v[208:209], v[218:219], 0, s[64:65]
	s_mov_b32 m0, s43
	s_nop 0
	global_load_lds_dwordx4 v[208:209], off
	s_waitcnt vmcnt(8)
	s_waitcnt lgkmcnt(0)
	s_setprio 1
	s_barrier
	v_mfma_f32_16x16x32_bf16 v[64:67], v[128:131], v[176:179], v[64:67]
	v_mfma_f32_16x16x32_bf16 v[64:67], v[132:135], v[180:183], v[64:67]
	v_mfma_f32_16x16x32_bf16 v[48:51], v[128:131], v[184:187], v[48:51]
	v_mfma_f32_16x16x32_bf16 v[48:51], v[132:135], v[188:191], v[48:51]
	v_mfma_f32_16x16x32_bf16 v[32:35], v[128:131], v[192:195], v[32:35]
	v_mfma_f32_16x16x32_bf16 v[32:35], v[132:135], v[196:199], v[32:35]
	v_mfma_f32_16x16x32_bf16 v[16:19], v[128:131], v[200:203], v[16:19]
	v_mfma_f32_16x16x32_bf16 v[16:19], v[132:135], v[204:207], v[16:19]
	v_mfma_f32_16x16x32_bf16 v[12:15], v[140:143], v[200:203], v[12:15]
	v_mfma_f32_16x16x32_bf16 v[12:15], v[148:151], v[204:207], v[12:15]
	v_mfma_f32_16x16x32_bf16 v[28:31], v[140:143], v[192:195], v[28:31]
	v_mfma_f32_16x16x32_bf16 v[28:31], v[148:151], v[196:199], v[28:31]
	v_mfma_f32_16x16x32_bf16 v[44:47], v[140:143], v[184:187], v[44:47]
	v_mfma_f32_16x16x32_bf16 v[44:47], v[148:151], v[188:191], v[44:47]
	v_mfma_f32_16x16x32_bf16 v[60:63], v[140:143], v[176:179], v[60:63]
	v_mfma_f32_16x16x32_bf16 v[60:63], v[148:151], v[180:183], v[60:63]
	s_setprio 0
	s_setprio 1
	v_mfma_f32_16x16x32_bf16 v[56:59], v[160:163], v[176:179], v[56:59]
	v_mfma_f32_16x16x32_bf16 v[56:59], v[164:167], v[180:183], v[56:59]
	v_mfma_f32_16x16x32_bf16 v[40:43], v[160:163], v[184:187], v[40:43]
	v_mfma_f32_16x16x32_bf16 v[40:43], v[164:167], v[188:191], v[40:43]
	v_mfma_f32_16x16x32_bf16 v[24:27], v[160:163], v[192:195], v[24:27]
	v_mfma_f32_16x16x32_bf16 v[24:27], v[164:167], v[196:199], v[24:27]
	v_mfma_f32_16x16x32_bf16 v[8:11], v[160:163], v[200:203], v[8:11]
	v_mfma_f32_16x16x32_bf16 v[8:11], v[164:167], v[204:207], v[8:11]
	s_add_i32 s50, s50, 2
	v_mfma_f32_16x16x32_bf16 v[4:7], v[168:171], v[200:203], v[4:7]
	v_mfma_f32_16x16x32_bf16 v[4:7], v[172:175], v[204:207], v[4:7]
	s_add_u32 s8, s8, 0x100
	s_addc_u32 s9, s9, 0
	v_mfma_f32_16x16x32_bf16 v[20:23], v[168:171], v[192:195], v[20:23]
	v_mfma_f32_16x16x32_bf16 v[20:23], v[172:175], v[196:199], v[20:23]
	s_cmp_gt_u32 s50, 29
	v_mfma_f32_16x16x32_bf16 v[36:39], v[168:171], v[184:187], v[36:39]
	v_mfma_f32_16x16x32_bf16 v[36:39], v[172:175], v[188:191], v[36:39]
	v_mfma_f32_16x16x32_bf16 v[52:55], v[168:171], v[176:179], v[52:55]
	v_mfma_f32_16x16x32_bf16 v[52:55], v[172:175], v[180:183], v[52:55]
	s_barrier
	s_setprio 0
	s_cbranch_scc0 .LBB0_2896
	s_cmpk_lt_u32 s22, 0x100
	s_cbranch_scc0 .LBB0_2899
	s_barrier

.LBB0_3116:
	v_add_u32_e32 v142, s26, v144
	ds_read_b128 v[146:149], v142
	ds_read_b128 v[150:153], v142 offset:1024
	ds_read_b128 v[154:157], v142 offset:2048
	ds_read_b128 v[158:161], v142 offset:3072
	v_add_u32_e32 v142, s40, v144
	ds_read_b128 v[162:165], v142
	ds_read_b128 v[166:169], v142 offset:1024
	ds_read_b128 v[170:173], v142 offset:2048
	ds_read_b128 v[174:177], v142 offset:3072
	s_add_u32 s18, s34, 0xfff80080
	s_addc_u32 s19, s35, -1
	s_cmp_eq_u32 s74, 28
	s_cselect_b32 s39, s13, s19
	s_cselect_b32 s38, s69, s18
	s_cselect_b32 s19, s11, s73
	s_cselect_b32 s18, s70, s71
	v_lshl_add_u64 v[142:143], s[34:35], 0, v[138:139]
	s_add_i32 m0, s43, 0xc000
	ds_read_b128 v[178:181], v145
	ds_read_b128 v[182:185], v145 offset:1024
	ds_read_b128 v[186:189], v145 offset:2048
	ds_read_b128 v[190:193], v145 offset:3072
	ds_read_b128 v[194:197], v145 offset:4096
	ds_read_b128 v[198:201], v145 offset:5120
	ds_read_b128 v[202:205], v145 offset:6144
	ds_read_b128 v[206:209], v145 offset:7168
	global_load_lds_dwordx4 v[142:143], off
	v_lshl_add_u64 v[142:143], s[34:35], 0, v[140:141]
	s_add_i32 m0, s43, 0xe000
	s_nop 0
	global_load_lds_dwordx4 v[142:143], off
	s_waitcnt vmcnt(8)
	s_waitcnt lgkmcnt(0)
	s_setprio 1
	s_barrier
	v_mfma_f32_16x16x32_bf16 v[128:131], v[146:149], v[178:181], v[128:131]
	v_mfma_f32_16x16x32_bf16 v[128:131], v[150:153], v[182:185], v[128:131]
	v_mfma_f32_16x16x32_bf16 v[112:115], v[146:149], v[186:189], v[112:115]
	v_mfma_f32_16x16x32_bf16 v[112:115], v[150:153], v[190:193], v[112:115]
	v_mfma_f32_16x16x32_bf16 v[96:99], v[146:149], v[194:197], v[96:99]
	v_mfma_f32_16x16x32_bf16 v[96:99], v[150:153], v[198:201], v[96:99]
	v_mfma_f32_16x16x32_bf16 v[80:83], v[146:149], v[202:205], v[80:83]
	v_mfma_f32_16x16x32_bf16 v[80:83], v[150:153], v[206:209], v[80:83]
	v_mfma_f32_16x16x32_bf16 v[72:75], v[154:157], v[202:205], v[72:75]
	v_mfma_f32_16x16x32_bf16 v[72:75], v[158:161], v[206:209], v[72:75]
	v_mfma_f32_16x16x32_bf16 v[88:91], v[154:157], v[194:197], v[88:91]
	v_mfma_f32_16x16x32_bf16 v[88:91], v[158:161], v[198:201], v[88:91]
	v_mfma_f32_16x16x32_bf16 v[104:107], v[154:157], v[186:189], v[104:107]
	v_mfma_f32_16x16x32_bf16 v[104:107], v[158:161], v[190:193], v[104:107]
	v_mfma_f32_16x16x32_bf16 v[120:123], v[154:157], v[178:181], v[120:123]
	v_mfma_f32_16x16x32_bf16 v[120:123], v[158:161], v[182:185], v[120:123]
	s_setprio 0
	s_setprio 1
	v_mfma_f32_16x16x32_bf16 v[124:127], v[162:165], v[178:181], v[124:127]
	v_mfma_f32_16x16x32_bf16 v[124:127], v[166:169], v[182:185], v[124:127]
	v_mfma_f32_16x16x32_bf16 v[108:111], v[162:165], v[186:189], v[108:111]
	v_mfma_f32_16x16x32_bf16 v[108:111], v[166:169], v[190:193], v[108:111]
	v_mfma_f32_16x16x32_bf16 v[92:95], v[162:165], v[194:197], v[92:95]
	v_mfma_f32_16x16x32_bf16 v[92:95], v[166:169], v[198:201], v[92:95]
	v_mfma_f32_16x16x32_bf16 v[76:79], v[162:165], v[202:205], v[76:79]
	v_mfma_f32_16x16x32_bf16 v[76:79], v[166:169], v[206:209], v[76:79]
	v_mfma_f32_16x16x32_bf16 v[68:71], v[170:173], v[202:205], v[68:71]
	v_mfma_f32_16x16x32_bf16 v[68:71], v[174:177], v[206:209], v[68:71]
	v_mfma_f32_16x16x32_bf16 v[84:87], v[170:173], v[194:197], v[84:87]
	v_mfma_f32_16x16x32_bf16 v[84:87], v[174:177], v[198:201], v[84:87]
	v_mfma_f32_16x16x32_bf16 v[100:103], v[170:173], v[186:189], v[100:103]
	v_mfma_f32_16x16x32_bf16 v[100:103], v[174:177], v[190:193], v[100:103]
	v_mfma_f32_16x16x32_bf16 v[116:119], v[170:173], v[178:181], v[116:119]
	v_mfma_f32_16x16x32_bf16 v[116:119], v[174:177], v[182:185], v[116:119]
	s_barrier
	s_setprio 0
	s_mov_b32 m0, s27
	v_lshl_add_u64 v[142:143], s[18:19], 0, v[2:3]
	s_add_u32 s76, s18, 0x80000
	ds_read_b128 v[178:181], v145 offset:16384
	ds_read_b128 v[182:185], v145 offset:17408
	ds_read_b128 v[186:189], v145 offset:18432
	ds_read_b128 v[190:193], v145 offset:19456
	ds_read_b128 v[194:197], v145 offset:20480
	ds_read_b128 v[198:201], v145 offset:21504
	ds_read_b128 v[202:205], v145 offset:22528
	ds_read_b128 v[206:209], v145 offset:23552
	global_load_lds_dwordx4 v[142:143], off
	v_lshl_add_u64 v[210:211], s[18:19], 0, v[132:133]
	s_mov_b32 m0, s37
	s_addc_u32 s77, s19, 0
	global_load_lds_dwordx4 v[210:211], off
	v_lshl_add_u64 v[212:213], s[76:77], 0, v[2:3]
	s_mov_b32 m0, s41
	v_lshl_add_u64 v[214:215], s[38:39], 0, v[134:135]
	global_load_lds_dwordx4 v[212:213], off
	v_lshl_add_u64 v[212:213], s[76:77], 0, v[132:133]
	s_mov_b32 m0, s42
	s_nop 0
	global_load_lds_dwordx4 v[212:213], off
	v_lshl_add_u64 v[212:213], s[38:39], 0, v[136:137]
	s_mov_b32 m0, s43
	s_nop 0
	global_load_lds_dwordx4 v[212:213], off
	s_mov_b32 m0, s44
	s_nop 0
	global_load_lds_dwordx4 v[214:215], off
	s_waitcnt vmcnt(8)
	s_waitcnt lgkmcnt(0)
	s_setprio 1
	s_barrier
	v_mfma_f32_16x16x32_bf16 v[64:67], v[146:149], v[178:181], v[64:67]
	v_mfma_f32_16x16x32_bf16 v[64:67], v[150:153], v[182:185], v[64:67]
	v_mfma_f32_16x16x32_bf16 v[48:51], v[146:149], v[186:189], v[48:51]
	v_mfma_f32_16x16x32_bf16 v[48:51], v[150:153], v[190:193], v[48:51]
	v_mfma_f32_16x16x32_bf16 v[32:35], v[146:149], v[194:197], v[32:35]
	v_mfma_f32_16x16x32_bf16 v[32:35], v[150:153], v[198:201], v[32:35]
	v_mfma_f32_16x16x32_bf16 v[16:19], v[146:149], v[202:205], v[16:19]
	v_mfma_f32_16x16x32_bf16 v[16:19], v[150:153], v[206:209], v[16:19]
	v_mfma_f32_16x16x32_bf16 v[8:11], v[154:157], v[202:205], v[8:11]
	v_mfma_f32_16x16x32_bf16 v[8:11], v[158:161], v[206:209], v[8:11]
	v_mfma_f32_16x16x32_bf16 v[24:27], v[154:157], v[194:197], v[24:27]
	v_mfma_f32_16x16x32_bf16 v[24:27], v[158:161], v[198:201], v[24:27]
	v_mfma_f32_16x16x32_bf16 v[40:43], v[154:157], v[186:189], v[40:43]
	v_mfma_f32_16x16x32_bf16 v[40:43], v[158:161], v[190:193], v[40:43]
	v_mfma_f32_16x16x32_bf16 v[56:59], v[154:157], v[178:181], v[56:59]
	v_mfma_f32_16x16x32_bf16 v[56:59], v[158:161], v[182:185], v[56:59]
	s_setprio 0
	s_setprio 1
	v_mfma_f32_16x16x32_bf16 v[60:63], v[162:165], v[178:181], v[60:63]
	v_mfma_f32_16x16x32_bf16 v[60:63], v[166:169], v[182:185], v[60:63]
	v_mfma_f32_16x16x32_bf16 v[44:47], v[162:165], v[186:189], v[44:47]
	v_mfma_f32_16x16x32_bf16 v[44:47], v[166:169], v[190:193], v[44:47]
	v_mfma_f32_16x16x32_bf16 v[28:31], v[162:165], v[194:197], v[28:31]
	v_mfma_f32_16x16x32_bf16 v[28:31], v[166:169], v[198:201], v[28:31]
	v_mfma_f32_16x16x32_bf16 v[12:15], v[162:165], v[202:205], v[12:15]
	v_mfma_f32_16x16x32_bf16 v[12:15], v[166:169], v[206:209], v[12:15]
	v_mfma_f32_16x16x32_bf16 v[4:7], v[170:173], v[202:205], v[4:7]
	v_mfma_f32_16x16x32_bf16 v[4:7], v[174:177], v[206:209], v[4:7]
	v_mfma_f32_16x16x32_bf16 v[20:23], v[170:173], v[194:197], v[20:23]
	v_mfma_f32_16x16x32_bf16 v[20:23], v[174:177], v[198:201], v[20:23]
	v_mfma_f32_16x16x32_bf16 v[36:39], v[170:173], v[186:189], v[36:39]
	v_mfma_f32_16x16x32_bf16 v[36:39], v[174:177], v[190:193], v[36:39]
	v_mfma_f32_16x16x32_bf16 v[52:55], v[170:173], v[178:181], v[52:55]
	v_mfma_f32_16x16x32_bf16 v[52:55], v[174:177], v[182:185], v[52:55]
	s_barrier
	s_setprio 0
	v_add_u32_e32 v158, s49, v144
	v_add_u32_e32 v174, s56, v144
	ds_read_b128 v[146:149], v158
	ds_read_b128 v[150:153], v158 offset:1024
	ds_read_b128 v[154:157], v158 offset:2048
	ds_read_b128 v[158:161], v158 offset:3072
	ds_read_b128 v[162:165], v174
	ds_read_b128 v[166:169], v174 offset:1024
	ds_read_b128 v[170:173], v174 offset:2048
	ds_read_b128 v[174:177], v174 offset:3072
	s_add_u32 s38, s38, 0x80000
	s_addc_u32 s39, s39, 0
	s_mov_b32 m0, s45
	v_lshl_add_u64 v[216:217], s[38:39], 0, v[136:137]
	ds_read_b128 v[178:181], v145 offset:32768
	ds_read_b128 v[182:185], v145 offset:33792
	ds_read_b128 v[186:189], v145 offset:34816
	ds_read_b128 v[190:193], v145 offset:35840
	ds_read_b128 v[194:197], v145 offset:36864
	ds_read_b128 v[198:201], v145 offset:37888
	ds_read_b128 v[202:205], v145 offset:38912
	ds_read_b128 v[206:209], v145 offset:39936
	global_load_lds_dwordx4 v[216:217], off
	v_lshl_add_u64 v[216:217], s[38:39], 0, v[134:135]
	s_mov_b32 m0, s46
	s_nop 0
	global_load_lds_dwordx4 v[216:217], off
	s_waitcnt vmcnt(8)
	s_waitcnt lgkmcnt(0)
	s_setprio 1
	s_barrier
	v_mfma_f32_16x16x32_bf16 v[128:131], v[146:149], v[178:181], v[128:131]
	v_mfma_f32_16x16x32_bf16 v[128:131], v[150:153], v[182:185], v[128:131]
	v_mfma_f32_16x16x32_bf16 v[112:115], v[146:149], v[186:189], v[112:115]
	v_mfma_f32_16x16x32_bf16 v[112:115], v[150:153], v[190:193], v[112:115]
	v_mfma_f32_16x16x32_bf16 v[96:99], v[146:149], v[194:197], v[96:99]
	v_mfma_f32_16x16x32_bf16 v[96:99], v[150:153], v[198:201], v[96:99]
	v_mfma_f32_16x16x32_bf16 v[80:83], v[146:149], v[202:205], v[80:83]
	v_mfma_f32_16x16x32_bf16 v[80:83], v[150:153], v[206:209], v[80:83]
	v_mfma_f32_16x16x32_bf16 v[72:75], v[154:157], v[202:205], v[72:75]
	v_mfma_f32_16x16x32_bf16 v[72:75], v[158:161], v[206:209], v[72:75]
	v_mfma_f32_16x16x32_bf16 v[88:91], v[154:157], v[194:197], v[88:91]
	v_mfma_f32_16x16x32_bf16 v[88:91], v[158:161], v[198:201], v[88:91]
	v_mfma_f32_16x16x32_bf16 v[104:107], v[154:157], v[186:189], v[104:107]
	v_mfma_f32_16x16x32_bf16 v[104:107], v[158:161], v[190:193], v[104:107]
	v_mfma_f32_16x16x32_bf16 v[120:123], v[154:157], v[178:181], v[120:123]
	v_mfma_f32_16x16x32_bf16 v[120:123], v[158:161], v[182:185], v[120:123]
	s_setprio 0
	s_setprio 1
	v_mfma_f32_16x16x32_bf16 v[124:127], v[162:165], v[178:181], v[124:127]
	v_mfma_f32_16x16x32_bf16 v[124:127], v[166:169], v[182:185], v[124:127]
	v_mfma_f32_16x16x32_bf16 v[108:111], v[162:165], v[186:189], v[108:111]
	v_mfma_f32_16x16x32_bf16 v[108:111], v[166:169], v[190:193], v[108:111]
	v_mfma_f32_16x16x32_bf16 v[92:95], v[162:165], v[194:197], v[92:95]
	v_mfma_f32_16x16x32_bf16 v[92:95], v[166:169], v[198:201], v[92:95]
	v_mfma_f32_16x16x32_bf16 v[76:79], v[162:165], v[202:205], v[76:79]
	v_mfma_f32_16x16x32_bf16 v[76:79], v[166:169], v[206:209], v[76:79]
	v_mfma_f32_16x16x32_bf16 v[68:71], v[170:173], v[202:205], v[68:71]
	v_mfma_f32_16x16x32_bf16 v[68:71], v[174:177], v[206:209], v[68:71]
	v_mfma_f32_16x16x32_bf16 v[84:87], v[170:173], v[194:197], v[84:87]
	v_mfma_f32_16x16x32_bf16 v[84:87], v[174:177], v[198:201], v[84:87]
	v_mfma_f32_16x16x32_bf16 v[100:103], v[170:173], v[186:189], v[100:103]
	v_mfma_f32_16x16x32_bf16 v[100:103], v[174:177], v[190:193], v[100:103]
	v_mfma_f32_16x16x32_bf16 v[116:119], v[170:173], v[178:181], v[116:119]
	v_mfma_f32_16x16x32_bf16 v[116:119], v[174:177], v[182:185], v[116:119]
	s_barrier
	s_setprio 0
	s_mov_b32 m0, s50
	v_lshl_add_u64 v[142:143], v[142:143], 0, s[64:65]
	s_add_u32 s18, s18, 0x80080
	ds_read_b128 v[178:181], v145 offset:49152
	ds_read_b128 v[182:185], v145 offset:50176
	ds_read_b128 v[186:189], v145 offset:51200
	ds_read_b128 v[190:193], v145 offset:52224
	ds_read_b128 v[194:197], v145 offset:53248
	ds_read_b128 v[198:201], v145 offset:54272
	ds_read_b128 v[202:205], v145 offset:55296
	ds_read_b128 v[206:209], v145 offset:56320
	global_load_lds_dwordx4 v[142:143], off
	v_lshl_add_u64 v[142:143], v[210:211], 0, s[64:65]
	s_mov_b32 m0, s51
	s_addc_u32 s19, s19, 0
	global_load_lds_dwordx4 v[142:143], off
	v_lshl_add_u64 v[142:143], s[18:19], 0, v[2:3]
	s_mov_b32 m0, s57
	s_nop 0
	global_load_lds_dwordx4 v[142:143], off
	v_lshl_add_u64 v[142:143], s[18:19], 0, v[132:133]
	s_mov_b32 m0, s58
	s_nop 0
	global_load_lds_dwordx4 v[142:143], off
	v_lshl_add_u64 v[142:143], v[212:213], 0, s[64:65]
	s_mov_b32 m0, s52
	s_nop 0
	global_load_lds_dwordx4 v[142:143], off
	v_lshl_add_u64 v[142:143], v[214:215], 0, s[64:65]
	s_mov_b32 m0, s53
	s_nop 0
	global_load_lds_dwordx4 v[142:143], off
	s_waitcnt vmcnt(8)
	s_waitcnt lgkmcnt(0)
	s_setprio 1
	s_barrier
	v_mfma_f32_16x16x32_bf16 v[64:67], v[146:149], v[178:181], v[64:67]
	v_mfma_f32_16x16x32_bf16 v[64:67], v[150:153], v[182:185], v[64:67]
	v_mfma_f32_16x16x32_bf16 v[48:51], v[146:149], v[186:189], v[48:51]
	v_mfma_f32_16x16x32_bf16 v[48:51], v[150:153], v[190:193], v[48:51]
	v_mfma_f32_16x16x32_bf16 v[32:35], v[146:149], v[194:197], v[32:35]
	v_mfma_f32_16x16x32_bf16 v[32:35], v[150:153], v[198:201], v[32:35]
	v_mfma_f32_16x16x32_bf16 v[16:19], v[146:149], v[202:205], v[16:19]
	v_mfma_f32_16x16x32_bf16 v[16:19], v[150:153], v[206:209], v[16:19]
	v_mfma_f32_16x16x32_bf16 v[8:11], v[154:157], v[202:205], v[8:11]
	v_mfma_f32_16x16x32_bf16 v[8:11], v[158:161], v[206:209], v[8:11]
	v_mfma_f32_16x16x32_bf16 v[24:27], v[154:157], v[194:197], v[24:27]
	v_mfma_f32_16x16x32_bf16 v[24:27], v[158:161], v[198:201], v[24:27]
	v_mfma_f32_16x16x32_bf16 v[40:43], v[154:157], v[186:189], v[40:43]
	v_mfma_f32_16x16x32_bf16 v[40:43], v[158:161], v[190:193], v[40:43]
	v_mfma_f32_16x16x32_bf16 v[56:59], v[154:157], v[178:181], v[56:59]
	v_mfma_f32_16x16x32_bf16 v[56:59], v[158:161], v[182:185], v[56:59]
	s_setprio 0
	s_setprio 1
	v_mfma_f32_16x16x32_bf16 v[60:63], v[162:165], v[178:181], v[60:63]
	v_mfma_f32_16x16x32_bf16 v[60:63], v[166:169], v[182:185], v[60:63]
	v_mfma_f32_16x16x32_bf16 v[44:47], v[162:165], v[186:189], v[44:47]
	v_mfma_f32_16x16x32_bf16 v[44:47], v[166:169], v[190:193], v[44:47]
	v_mfma_f32_16x16x32_bf16 v[28:31], v[162:165], v[194:197], v[28:31]
	v_mfma_f32_16x16x32_bf16 v[28:31], v[166:169], v[198:201], v[28:31]
	v_mfma_f32_16x16x32_bf16 v[12:15], v[162:165], v[202:205], v[12:15]
	v_mfma_f32_16x16x32_bf16 v[12:15], v[166:169], v[206:209], v[12:15]
	s_add_i32 s74, s74, 2
	v_mfma_f32_16x16x32_bf16 v[4:7], v[170:173], v[202:205], v[4:7]
	v_mfma_f32_16x16x32_bf16 v[4:7], v[174:177], v[206:209], v[4:7]
	s_add_u32 s34, s34, 0x100
	s_addc_u32 s35, s35, 0
	v_mfma_f32_16x16x32_bf16 v[20:23], v[170:173], v[194:197], v[20:23]
	v_mfma_f32_16x16x32_bf16 v[20:23], v[174:177], v[198:201], v[20:23]
	s_add_u32 s71, s71, 0x100
	s_addc_u32 s73, s73, 0
	v_mfma_f32_16x16x32_bf16 v[36:39], v[170:173], v[186:189], v[36:39]
	v_mfma_f32_16x16x32_bf16 v[36:39], v[174:177], v[190:193], v[36:39]
	s_cmp_gt_u32 s74, 29
	v_mfma_f32_16x16x32_bf16 v[52:55], v[170:173], v[178:181], v[52:55]
	v_mfma_f32_16x16x32_bf16 v[52:55], v[174:177], v[182:185], v[52:55]
	s_barrier
	s_setprio 0
	s_cbranch_scc0 .LBB0_3116
	s_and_b64 vcc, exec, s[8:9]
	s_cbranch_vccz .LBB0_3119
	s_barrier

.LBB0_3195:
	v_add_u32_e32 v144, s26, v249
	v_add_u32_e32 v160, s38, v249
	ds_read_b128 v[132:135], v144
	ds_read_b128 v[136:139], v144 offset:1024
	ds_read_b128 v[140:143], v144 offset:2048
	ds_read_b128 v[144:147], v144 offset:3072
	ds_read_b128 v[148:151], v160
	ds_read_b128 v[152:155], v160 offset:1024
	ds_read_b128 v[156:159], v160 offset:2048
	ds_read_b128 v[160:163], v160 offset:3072
	s_add_u32 s24, s14, 0x100
	s_addc_u32 s25, s15, 0
	s_cmpk_eq_i32 s74, 0x54
	s_cselect_b32 s35, s5, s25
	s_cselect_b32 s34, s4, s24
	s_cselect_b32 s19, s13, s73
	s_cselect_b32 s18, s12, s71
	v_lshl_add_u64 v[196:197], s[14:15], 0, v[222:223]
	s_add_i32 m0, s41, 0xc000
	ds_read_b128 v[164:167], v250
	ds_read_b128 v[168:171], v250 offset:1024
	ds_read_b128 v[172:175], v250 offset:2048
	ds_read_b128 v[176:179], v250 offset:3072
	ds_read_b128 v[180:183], v250 offset:4096
	ds_read_b128 v[184:187], v250 offset:5120
	ds_read_b128 v[188:191], v250 offset:6144
	ds_read_b128 v[192:195], v250 offset:7168
	global_load_lds_dwordx4 v[196:197], off
	v_lshl_add_u64 v[196:197], s[14:15], 0, v[224:225]
	s_add_i32 m0, s41, 0xe000
	s_nop 0
	global_load_lds_dwordx4 v[196:197], off
	s_waitcnt vmcnt(8)
	s_waitcnt lgkmcnt(0)
	s_setprio 1
	s_barrier
	v_mfma_f32_16x16x32_bf16 v[128:131], v[132:135], v[164:167], v[128:131]
	v_mfma_f32_16x16x32_bf16 v[128:131], v[136:139], v[168:171], v[128:131]
	v_mfma_f32_16x16x32_bf16 v[112:115], v[132:135], v[172:175], v[112:115]
	v_mfma_f32_16x16x32_bf16 v[112:115], v[136:139], v[176:179], v[112:115]
	v_mfma_f32_16x16x32_bf16 v[96:99], v[132:135], v[180:183], v[96:99]
	v_mfma_f32_16x16x32_bf16 v[96:99], v[136:139], v[184:187], v[96:99]
	v_mfma_f32_16x16x32_bf16 v[80:83], v[132:135], v[188:191], v[80:83]
	v_mfma_f32_16x16x32_bf16 v[80:83], v[136:139], v[192:195], v[80:83]
	v_mfma_f32_16x16x32_bf16 v[76:79], v[140:143], v[188:191], v[76:79]
	v_mfma_f32_16x16x32_bf16 v[76:79], v[144:147], v[192:195], v[76:79]
	v_mfma_f32_16x16x32_bf16 v[92:95], v[140:143], v[180:183], v[92:95]
	v_mfma_f32_16x16x32_bf16 v[92:95], v[144:147], v[184:187], v[92:95]
	v_mfma_f32_16x16x32_bf16 v[108:111], v[140:143], v[172:175], v[108:111]
	v_mfma_f32_16x16x32_bf16 v[108:111], v[144:147], v[176:179], v[108:111]
	v_mfma_f32_16x16x32_bf16 v[124:127], v[140:143], v[164:167], v[124:127]
	v_mfma_f32_16x16x32_bf16 v[124:127], v[144:147], v[168:171], v[124:127]
	s_setprio 0
	s_setprio 1
	v_mfma_f32_16x16x32_bf16 v[120:123], v[148:151], v[164:167], v[120:123]
	v_mfma_f32_16x16x32_bf16 v[120:123], v[152:155], v[168:171], v[120:123]
	v_mfma_f32_16x16x32_bf16 v[104:107], v[148:151], v[172:175], v[104:107]
	v_mfma_f32_16x16x32_bf16 v[104:107], v[152:155], v[176:179], v[104:107]
	v_mfma_f32_16x16x32_bf16 v[88:91], v[148:151], v[180:183], v[88:91]
	v_mfma_f32_16x16x32_bf16 v[88:91], v[152:155], v[184:187], v[88:91]
	v_mfma_f32_16x16x32_bf16 v[72:75], v[148:151], v[188:191], v[72:75]
	v_mfma_f32_16x16x32_bf16 v[72:75], v[152:155], v[192:195], v[72:75]
	v_mfma_f32_16x16x32_bf16 v[68:71], v[156:159], v[188:191], v[68:71]
	v_mfma_f32_16x16x32_bf16 v[68:71], v[160:163], v[192:195], v[68:71]
	v_mfma_f32_16x16x32_bf16 v[84:87], v[156:159], v[180:183], v[84:87]
	v_mfma_f32_16x16x32_bf16 v[84:87], v[160:163], v[184:187], v[84:87]
	v_mfma_f32_16x16x32_bf16 v[100:103], v[156:159], v[172:175], v[100:103]
	v_mfma_f32_16x16x32_bf16 v[100:103], v[160:163], v[176:179], v[100:103]
	v_mfma_f32_16x16x32_bf16 v[116:119], v[156:159], v[164:167], v[116:119]
	v_mfma_f32_16x16x32_bf16 v[116:119], v[160:163], v[168:171], v[116:119]
	s_barrier
	s_setprio 0
	s_mov_b32 m0, s27
	v_lshl_add_u64 v[196:197], s[18:19], 0, v[2:3]
	s_add_u32 s14, s18, 0x160000
	ds_read_b128 v[164:167], v250 offset:16384
	ds_read_b128 v[168:171], v250 offset:17408
	ds_read_b128 v[172:175], v250 offset:18432
	ds_read_b128 v[176:179], v250 offset:19456
	ds_read_b128 v[180:183], v250 offset:20480
	ds_read_b128 v[184:187], v250 offset:21504
	ds_read_b128 v[188:191], v250 offset:22528
	ds_read_b128 v[192:195], v250 offset:23552
	global_load_lds_dwordx4 v[196:197], off
	v_lshl_add_u64 v[198:199], s[18:19], 0, v[216:217]
	s_mov_b32 m0, s37
	s_addc_u32 s15, s19, 0
	global_load_lds_dwordx4 v[198:199], off
	v_lshl_add_u64 v[200:201], s[14:15], 0, v[2:3]
	s_mov_b32 m0, s39
	v_lshl_add_u64 v[202:203], s[34:35], 0, v[218:219]
	global_load_lds_dwordx4 v[200:201], off
	v_lshl_add_u64 v[200:201], s[14:15], 0, v[216:217]
	s_mov_b32 m0, s40
	s_nop 0
	global_load_lds_dwordx4 v[200:201], off
	v_lshl_add_u64 v[200:201], s[34:35], 0, v[220:221]
	s_mov_b32 m0, s41
	s_nop 0
	global_load_lds_dwordx4 v[200:201], off
	s_mov_b32 m0, s42
	s_nop 0
	global_load_lds_dwordx4 v[202:203], off
	s_waitcnt vmcnt(8)
	s_waitcnt lgkmcnt(0)
	s_setprio 1
	s_barrier
	v_mfma_f32_16x16x32_bf16 v[64:67], v[132:135], v[164:167], v[64:67]
	v_mfma_f32_16x16x32_bf16 v[64:67], v[136:139], v[168:171], v[64:67]
	v_mfma_f32_16x16x32_bf16 v[48:51], v[132:135], v[172:175], v[48:51]
	v_mfma_f32_16x16x32_bf16 v[48:51], v[136:139], v[176:179], v[48:51]
	v_mfma_f32_16x16x32_bf16 v[32:35], v[132:135], v[180:183], v[32:35]
	v_mfma_f32_16x16x32_bf16 v[32:35], v[136:139], v[184:187], v[32:35]
	v_mfma_f32_16x16x32_bf16 v[16:19], v[132:135], v[188:191], v[16:19]
	v_mfma_f32_16x16x32_bf16 v[16:19], v[136:139], v[192:195], v[16:19]
	v_mfma_f32_16x16x32_bf16 v[12:15], v[140:143], v[188:191], v[12:15]
	v_mfma_f32_16x16x32_bf16 v[12:15], v[144:147], v[192:195], v[12:15]
	v_mfma_f32_16x16x32_bf16 v[28:31], v[140:143], v[180:183], v[28:31]
	v_mfma_f32_16x16x32_bf16 v[28:31], v[144:147], v[184:187], v[28:31]
	v_mfma_f32_16x16x32_bf16 v[44:47], v[140:143], v[172:175], v[44:47]
	v_mfma_f32_16x16x32_bf16 v[44:47], v[144:147], v[176:179], v[44:47]
	v_mfma_f32_16x16x32_bf16 v[60:63], v[140:143], v[164:167], v[60:63]
	v_mfma_f32_16x16x32_bf16 v[60:63], v[144:147], v[168:171], v[60:63]
	s_setprio 0
	s_setprio 1
	v_mfma_f32_16x16x32_bf16 v[56:59], v[148:151], v[164:167], v[56:59]
	v_mfma_f32_16x16x32_bf16 v[56:59], v[152:155], v[168:171], v[56:59]
	v_mfma_f32_16x16x32_bf16 v[40:43], v[148:151], v[172:175], v[40:43]
	v_mfma_f32_16x16x32_bf16 v[40:43], v[152:155], v[176:179], v[40:43]
	v_mfma_f32_16x16x32_bf16 v[24:27], v[148:151], v[180:183], v[24:27]
	v_mfma_f32_16x16x32_bf16 v[24:27], v[152:155], v[184:187], v[24:27]
	v_mfma_f32_16x16x32_bf16 v[8:11], v[148:151], v[188:191], v[8:11]
	v_mfma_f32_16x16x32_bf16 v[8:11], v[152:155], v[192:195], v[8:11]
	v_mfma_f32_16x16x32_bf16 v[4:7], v[156:159], v[188:191], v[4:7]
	v_mfma_f32_16x16x32_bf16 v[4:7], v[160:163], v[192:195], v[4:7]
	v_mfma_f32_16x16x32_bf16 v[20:23], v[156:159], v[180:183], v[20:23]
	v_mfma_f32_16x16x32_bf16 v[20:23], v[160:163], v[184:187], v[20:23]
	v_mfma_f32_16x16x32_bf16 v[36:39], v[156:159], v[172:175], v[36:39]
	v_mfma_f32_16x16x32_bf16 v[36:39], v[160:163], v[176:179], v[36:39]
	v_mfma_f32_16x16x32_bf16 v[52:55], v[156:159], v[164:167], v[52:55]
	v_mfma_f32_16x16x32_bf16 v[52:55], v[160:163], v[168:171], v[52:55]
	s_barrier
	s_setprio 0
	v_add_u32_e32 v144, s49, v249
	v_add_u32_e32 v160, s56, v249
	ds_read_b128 v[132:135], v144
	ds_read_b128 v[136:139], v144 offset:1024
	ds_read_b128 v[140:143], v144 offset:2048
	ds_read_b128 v[144:147], v144 offset:3072
	ds_read_b128 v[148:151], v160
	ds_read_b128 v[152:155], v160 offset:1024
	ds_read_b128 v[156:159], v160 offset:2048
	ds_read_b128 v[160:163], v160 offset:3072
	s_add_u32 s14, s34, 0x160000
	s_addc_u32 s15, s35, 0
	s_mov_b32 m0, s43
	v_lshl_add_u64 v[204:205], s[14:15], 0, v[220:221]
	ds_read_b128 v[164:167], v250 offset:32768
	ds_read_b128 v[168:171], v250 offset:33792
	ds_read_b128 v[172:175], v250 offset:34816
	ds_read_b128 v[176:179], v250 offset:35840
	ds_read_b128 v[180:183], v250 offset:36864
	ds_read_b128 v[184:187], v250 offset:37888
	ds_read_b128 v[188:191], v250 offset:38912
	ds_read_b128 v[192:195], v250 offset:39936
	global_load_lds_dwordx4 v[204:205], off
	v_lshl_add_u64 v[204:205], s[14:15], 0, v[218:219]
	s_mov_b32 m0, s44
	s_nop 0
	global_load_lds_dwordx4 v[204:205], off
	s_waitcnt vmcnt(8)
	s_waitcnt lgkmcnt(0)
	s_setprio 1
	s_barrier
	v_mfma_f32_16x16x32_bf16 v[128:131], v[132:135], v[164:167], v[128:131]
	v_mfma_f32_16x16x32_bf16 v[128:131], v[136:139], v[168:171], v[128:131]
	v_mfma_f32_16x16x32_bf16 v[112:115], v[132:135], v[172:175], v[112:115]
	v_mfma_f32_16x16x32_bf16 v[112:115], v[136:139], v[176:179], v[112:115]
	v_mfma_f32_16x16x32_bf16 v[96:99], v[132:135], v[180:183], v[96:99]
	v_mfma_f32_16x16x32_bf16 v[96:99], v[136:139], v[184:187], v[96:99]
	v_mfma_f32_16x16x32_bf16 v[80:83], v[132:135], v[188:191], v[80:83]
	v_mfma_f32_16x16x32_bf16 v[80:83], v[136:139], v[192:195], v[80:83]
	v_mfma_f32_16x16x32_bf16 v[76:79], v[140:143], v[188:191], v[76:79]
	v_mfma_f32_16x16x32_bf16 v[76:79], v[144:147], v[192:195], v[76:79]
	v_mfma_f32_16x16x32_bf16 v[92:95], v[140:143], v[180:183], v[92:95]
	v_mfma_f32_16x16x32_bf16 v[92:95], v[144:147], v[184:187], v[92:95]
	v_mfma_f32_16x16x32_bf16 v[108:111], v[140:143], v[172:175], v[108:111]
	v_mfma_f32_16x16x32_bf16 v[108:111], v[144:147], v[176:179], v[108:111]
	v_mfma_f32_16x16x32_bf16 v[124:127], v[140:143], v[164:167], v[124:127]
	v_mfma_f32_16x16x32_bf16 v[124:127], v[144:147], v[168:171], v[124:127]
	s_setprio 0
	s_setprio 1
	v_mfma_f32_16x16x32_bf16 v[120:123], v[148:151], v[164:167], v[120:123]
	v_mfma_f32_16x16x32_bf16 v[120:123], v[152:155], v[168:171], v[120:123]
	v_mfma_f32_16x16x32_bf16 v[104:107], v[148:151], v[172:175], v[104:107]
	v_mfma_f32_16x16x32_bf16 v[104:107], v[152:155], v[176:179], v[104:107]
	v_mfma_f32_16x16x32_bf16 v[88:91], v[148:151], v[180:183], v[88:91]
	v_mfma_f32_16x16x32_bf16 v[88:91], v[152:155], v[184:187], v[88:91]
	v_mfma_f32_16x16x32_bf16 v[72:75], v[148:151], v[188:191], v[72:75]
	v_mfma_f32_16x16x32_bf16 v[72:75], v[152:155], v[192:195], v[72:75]
	v_mfma_f32_16x16x32_bf16 v[68:71], v[156:159], v[188:191], v[68:71]
	v_mfma_f32_16x16x32_bf16 v[68:71], v[160:163], v[192:195], v[68:71]
	v_mfma_f32_16x16x32_bf16 v[84:87], v[156:159], v[180:183], v[84:87]
	v_mfma_f32_16x16x32_bf16 v[84:87], v[160:163], v[184:187], v[84:87]
	v_mfma_f32_16x16x32_bf16 v[100:103], v[156:159], v[172:175], v[100:103]
	v_mfma_f32_16x16x32_bf16 v[100:103], v[160:163], v[176:179], v[100:103]
	v_mfma_f32_16x16x32_bf16 v[116:119], v[156:159], v[164:167], v[116:119]
	v_mfma_f32_16x16x32_bf16 v[116:119], v[160:163], v[168:171], v[116:119]
	s_barrier
	s_setprio 0
	s_mov_b32 m0, s50
	v_lshl_add_u64 v[196:197], v[196:197], 0, s[64:65]
	s_add_u32 s14, s18, 0x160080
	ds_read_b128 v[164:167], v250 offset:49152
	ds_read_b128 v[168:171], v250 offset:50176
	ds_read_b128 v[172:175], v250 offset:51200
	ds_read_b128 v[176:179], v250 offset:52224
	ds_read_b128 v[180:183], v250 offset:53248
	ds_read_b128 v[184:187], v250 offset:54272
	ds_read_b128 v[188:191], v250 offset:55296
	ds_read_b128 v[192:195], v250 offset:56320
	global_load_lds_dwordx4 v[196:197], off
	v_lshl_add_u64 v[196:197], v[198:199], 0, s[64:65]
	s_mov_b32 m0, s51
	s_addc_u32 s15, s19, 0
	global_load_lds_dwordx4 v[196:197], off
	v_lshl_add_u64 v[196:197], s[14:15], 0, v[2:3]
	s_mov_b32 m0, s57
	s_nop 0
	global_load_lds_dwordx4 v[196:197], off
	v_lshl_add_u64 v[196:197], s[14:15], 0, v[216:217]
	s_mov_b32 m0, s58
	s_nop 0
	global_load_lds_dwordx4 v[196:197], off
	v_lshl_add_u64 v[196:197], v[200:201], 0, s[64:65]
	s_mov_b32 m0, s52
	s_nop 0
	global_load_lds_dwordx4 v[196:197], off
	v_lshl_add_u64 v[196:197], v[202:203], 0, s[64:65]
	s_mov_b32 m0, s53
	s_nop 0
	global_load_lds_dwordx4 v[196:197], off
	s_waitcnt vmcnt(8)
	s_waitcnt lgkmcnt(0)
	s_setprio 1
	s_barrier
	v_mfma_f32_16x16x32_bf16 v[64:67], v[132:135], v[164:167], v[64:67]
	v_mfma_f32_16x16x32_bf16 v[64:67], v[136:139], v[168:171], v[64:67]
	v_mfma_f32_16x16x32_bf16 v[48:51], v[132:135], v[172:175], v[48:51]
	v_mfma_f32_16x16x32_bf16 v[48:51], v[136:139], v[176:179], v[48:51]
	v_mfma_f32_16x16x32_bf16 v[32:35], v[132:135], v[180:183], v[32:35]
	v_mfma_f32_16x16x32_bf16 v[32:35], v[136:139], v[184:187], v[32:35]
	v_mfma_f32_16x16x32_bf16 v[16:19], v[132:135], v[188:191], v[16:19]
	v_mfma_f32_16x16x32_bf16 v[16:19], v[136:139], v[192:195], v[16:19]
	v_mfma_f32_16x16x32_bf16 v[12:15], v[140:143], v[188:191], v[12:15]
	v_mfma_f32_16x16x32_bf16 v[12:15], v[144:147], v[192:195], v[12:15]
	v_mfma_f32_16x16x32_bf16 v[28:31], v[140:143], v[180:183], v[28:31]
	v_mfma_f32_16x16x32_bf16 v[28:31], v[144:147], v[184:187], v[28:31]
	v_mfma_f32_16x16x32_bf16 v[44:47], v[140:143], v[172:175], v[44:47]
	v_mfma_f32_16x16x32_bf16 v[44:47], v[144:147], v[176:179], v[44:47]
	v_mfma_f32_16x16x32_bf16 v[60:63], v[140:143], v[164:167], v[60:63]
	v_mfma_f32_16x16x32_bf16 v[60:63], v[144:147], v[168:171], v[60:63]
	s_setprio 0
	s_setprio 1
	v_mfma_f32_16x16x32_bf16 v[56:59], v[148:151], v[164:167], v[56:59]
	v_mfma_f32_16x16x32_bf16 v[56:59], v[152:155], v[168:171], v[56:59]
	v_mfma_f32_16x16x32_bf16 v[40:43], v[148:151], v[172:175], v[40:43]
	v_mfma_f32_16x16x32_bf16 v[40:43], v[152:155], v[176:179], v[40:43]
	v_mfma_f32_16x16x32_bf16 v[24:27], v[148:151], v[180:183], v[24:27]
	v_mfma_f32_16x16x32_bf16 v[24:27], v[152:155], v[184:187], v[24:27]
	v_mfma_f32_16x16x32_bf16 v[8:11], v[148:151], v[188:191], v[8:11]
	v_mfma_f32_16x16x32_bf16 v[8:11], v[152:155], v[192:195], v[8:11]
	s_add_i32 s74, s74, 2
	v_mfma_f32_16x16x32_bf16 v[4:7], v[156:159], v[188:191], v[4:7]
	v_mfma_f32_16x16x32_bf16 v[4:7], v[160:163], v[192:195], v[4:7]
	s_add_u32 s71, s71, 0x100
	s_addc_u32 s73, s73, 0
	v_mfma_f32_16x16x32_bf16 v[20:23], v[156:159], v[180:183], v[20:23]
	v_mfma_f32_16x16x32_bf16 v[20:23], v[160:163], v[184:187], v[20:23]
	s_cmpk_gt_u32 s74, 0x55
	v_mfma_f32_16x16x32_bf16 v[36:39], v[156:159], v[172:175], v[36:39]
	v_mfma_f32_16x16x32_bf16 v[36:39], v[160:163], v[176:179], v[36:39]
	v_mfma_f32_16x16x32_bf16 v[52:55], v[156:159], v[164:167], v[52:55]
	v_mfma_f32_16x16x32_bf16 v[52:55], v[160:163], v[168:171], v[52:55]
	s_barrier
	s_setprio 0
	s_mov_b64 s[14:15], s[24:25]
	s_cbranch_scc0 .LBB0_3195
	s_and_b64 vcc, exec, s[10:11]
	s_cbranch_vccz .LBB0_3198
	s_barrier
